# GEMM tile stores (C, M2, P1): sixteen LDS row reads issued up front, counted waits, scalar-stride store addresses; N2 uniform state fully scalar
# baseline (speedup 1.0000x reference)
; #define TIDX512 launder_i((int)threadIdx.x)
; __device__ __forceinline__ void epi_store(const char* lds, bf16_t* __restrict__ O, int ldo, int m0, int n0, int ncols_valid) {
;     const int t = TIDX512;
;     const int chunk = t & 31, rsub = t >> 5;
;     if (n0 + chunk * 8 < ncols_valid) {
; #pragma unroll
;         for (int ps = 0; ps < 16; ps++) {
;             const int row = ps * 16 + rsub;
;             const u32x4 v = *(const u32x4*)(lds + row * EPI_ROWB + chunk * 16);
;             *(u32x4*)(O + (size_t)(m0 + row) * ldo + n0 + chunk * 8) = v;
;         }
;     }
; }
.LBB0_321:
	s_or_b64 exec, exec, s[8:9]
	v_mov_b32_e32 v2, v158
	s_waitcnt lgkmcnt(0)
	s_barrier
	s_nop 0
	v_and_b32_e32 v0, 31, v2
	v_lshlrev_b32_e32 v1, 3, v0
	v_or_b32_e32 v3, s44, v1
	v_cmp_gt_i32_e32 vcc, s71, v3
	s_and_saveexec_b64 s[8:9], vcc
	s_cbranch_execz .LBB0_289
	v_ashrrev_i32_e32 v4, 5, v2
	v_lshlrev_b32_e32 v128, 1, v1
	v_mul_lo_u32 v1, v4, s3
	s_ashr_i32 s45, s44, 31
	v_lshl_add_u32 v12, v0, 4, v1
	v_add_u32_e32 v31, 0x10800, v12
	ds_read_b128 v[32:35], v12
	ds_read_b128 v[36:39], v12 offset:8448
	ds_read_b128 v[40:43], v12 offset:16896
	ds_read_b128 v[44:47], v12 offset:25344
	ds_read_b128 v[48:51], v12 offset:33792
	ds_read_b128 v[52:55], v12 offset:42240
	ds_read_b128 v[56:59], v12 offset:50688
	ds_read_b128 v[60:63], v12 offset:59136
	ds_read_b128 v[64:67], v31
	ds_read_b128 v[68:71], v31 offset:8448
	ds_read_b128 v[72:75], v31 offset:16896
	ds_read_b128 v[76:79], v31 offset:25344
	ds_read_b128 v[80:83], v31 offset:33792
	ds_read_b128 v[84:87], v31 offset:42240
	ds_read_b128 v[88:91], v31 offset:50688
	s_lshl_b64 s[44:45], s[44:45], 1
	s_add_u32 s44, s1, s44
	s_addc_u32 s45, s2, s45
	v_add_u32_e32 v13, s82, v4
	v_lshl_add_u64 v[8:9], s[44:45], 0, v[128:129]
	v_mad_i64_i32 v[10:11], s[44:45], v13, s72, v[8:9]
	s_lshl_b32 s86, s72, 4
	s_mov_b32 s87, 0
	s_waitcnt lgkmcnt(14)
	global_store_dwordx4 v[10:11], v[32:35], off
	ds_read_b128 v[92:95], v31 offset:59136
	v_lshl_add_u64 v[10:11], v[10:11], 0, s[86:87]
	s_waitcnt lgkmcnt(14)
	global_store_dwordx4 v[10:11], v[36:39], off
	v_lshl_add_u64 v[10:11], v[10:11], 0, s[86:87]
	s_waitcnt lgkmcnt(13)
	global_store_dwordx4 v[10:11], v[40:43], off
	v_lshl_add_u64 v[10:11], v[10:11], 0, s[86:87]
	s_waitcnt lgkmcnt(12)
	global_store_dwordx4 v[10:11], v[44:47], off
	v_lshl_add_u64 v[10:11], v[10:11], 0, s[86:87]
	s_waitcnt lgkmcnt(11)
	global_store_dwordx4 v[10:11], v[48:51], off
	v_lshl_add_u64 v[10:11], v[10:11], 0, s[86:87]
	s_waitcnt lgkmcnt(10)
	global_store_dwordx4 v[10:11], v[52:55], off
	v_lshl_add_u64 v[10:11], v[10:11], 0, s[86:87]
	s_waitcnt lgkmcnt(9)
	global_store_dwordx4 v[10:11], v[56:59], off
	v_lshl_add_u64 v[10:11], v[10:11], 0, s[86:87]
	s_waitcnt lgkmcnt(8)
	global_store_dwordx4 v[10:11], v[60:63], off
	v_lshl_add_u64 v[10:11], v[10:11], 0, s[86:87]
	s_waitcnt lgkmcnt(7)
	global_store_dwordx4 v[10:11], v[64:67], off
	v_lshl_add_u64 v[10:11], v[10:11], 0, s[86:87]
	s_waitcnt lgkmcnt(6)
	global_store_dwordx4 v[10:11], v[68:71], off
	v_lshl_add_u64 v[10:11], v[10:11], 0, s[86:87]
	s_waitcnt lgkmcnt(5)
	global_store_dwordx4 v[10:11], v[72:75], off
	v_lshl_add_u64 v[10:11], v[10:11], 0, s[86:87]
	s_waitcnt lgkmcnt(4)
	global_store_dwordx4 v[10:11], v[76:79], off
	v_lshl_add_u64 v[10:11], v[10:11], 0, s[86:87]
	s_waitcnt lgkmcnt(3)
	global_store_dwordx4 v[10:11], v[80:83], off
	v_lshl_add_u64 v[10:11], v[10:11], 0, s[86:87]
	s_waitcnt lgkmcnt(2)
	global_store_dwordx4 v[10:11], v[84:87], off
	v_lshl_add_u64 v[10:11], v[10:11], 0, s[86:87]
	s_waitcnt lgkmcnt(1)
	global_store_dwordx4 v[10:11], v[88:91], off
	v_lshl_add_u64 v[10:11], v[10:11], 0, s[86:87]
	s_waitcnt lgkmcnt(0)
	global_store_dwordx4 v[10:11], v[92:95], off
	s_branch .LBB0_289

; #define TIDX512 launder_i((int)threadIdx.x)
; __device__ __forceinline__ void gemm_issue(const GemmSrc& g, int kt, int s, char* lds) {
;     const int tid = TIDX512, lane = tid & 63, wave = tid >> 6;
;     char* xdst = lds + s * 65536 + wave * 4096 + lane * 16;
;     char* wdst = xdst + 32768;
; #pragma unroll
;     for (int i = 0; i < 4; i++) {
;         const int d = (i & 1) ? g.dsw : 0;
; __device__ __forceinline__ void gemm_mainloop(f32x4 (&acc)[8][4], const GemmSrc& g, int K, char* lds) {
;     ...
;     for (int kt = 0; kt < KT; kt++) {
;         WAIT_V(0);
;         __builtin_amdgcn_s_barrier();
;         const char* st = lds + (kt & 1) * 65536;
;         bf16x8 afA[4], afB[4], bX[4], bY[4];
; #pragma unroll
;         for (int ni = 0; ni < 4; ni++) afA[ni] = *(const bf16x8*)(st + woff + ni * 16 * 128 + rdo0);
; #pragma unroll
;         for (int mi = 0; mi < 4; mi++) bX[mi] = *(const bf16x8*)(st + xoff + mi * 16 * 128 + rdo0);
;         if (kt + 1 < KT) gemm_issue(g, kt + 1, (kt + 1) & 1, lds);
; #pragma unroll
;         for (int mi = 0; mi < 4; mi++) bY[mi] = *(const bf16x8*)(st + xoff + (4 + mi) * 16 * 128 + rdo0);
; #pragma unroll
;         for (int ni = 0; ni < 4; ni++) afB[ni] = *(const bf16x8*)(st + woff + ni * 16 * 128 + rdo1);
; #pragma unroll
;         for (int mi = 0; mi < 4; mi++)
; #pragma unroll
;             for (int ni = 0; ni < 4; ni++) acc[mi][ni] = mfma16(afA[ni], bX[mi], acc[mi][ni]);
;         __builtin_amdgcn_sched_barrier(0);
; #pragma unroll
;         for (int mi = 0; mi < 4; mi++) bX[mi] = *(const bf16x8*)(st + xoff + mi * 16 * 128 + rdo1);
; #pragma unroll
;         for (int mi = 0; mi < 4; mi++)
; #pragma unroll
;             for (int ni = 0; ni < 4; ni++) acc[4 + mi][ni] = mfma16(afA[ni], bY[mi], acc[4 + mi][ni]);
;         __builtin_amdgcn_sched_barrier(0);
; #pragma unroll
;         for (int mi = 0; mi < 4; mi++) bY[mi] = *(const bf16x8*)(st + xoff + (4 + mi) * 16 * 128 + rdo1);
; #pragma unroll
;         for (int mi = 0; mi < 4; mi++)
; #pragma unroll
;             for (int ni = 0; ni < 4; ni++) acc[mi][ni] = mfma16(afB[ni], bX[mi], acc[mi][ni]);
;         __builtin_amdgcn_sched_barrier(0);
; #pragma unroll
;         for (int mi = 0; mi < 4; mi++)
; #pragma unroll
;             for (int ni = 0; ni < 4; ni++) acc[4 + mi][ni] = mfma16(afB[ni], bY[mi], acc[4 + mi][ni]);
;         __builtin_amdgcn_sched_barrier(0);
.LBB0_787:
	s_add_i32 s48, s39, 0xffff0000
	s_and_b32 s48, s48, 0x10000
	v_or_b32_e32 v152, s48, v139
	v_add_u32_e32 v200, s48, v138
	v_add_u32_e32 v154, v152, v137
	v_add_u32_e32 v188, v200, v137
	v_mov_b32_e32 v180, v158
	s_waitcnt vmcnt(0)
	s_barrier
	ds_read_b128 v[140:143], v154 offset:32768
	ds_read_b128 v[144:147], v154 offset:34816
	ds_read_b128 v[148:151], v154 offset:36864
	ds_read_b128 v[154:157], v154 offset:38912
	ds_read_b128 v[164:167], v188
	ds_read_b128 v[168:171], v188 offset:2048
	ds_read_b128 v[172:175], v188 offset:4096
	ds_read_b128 v[176:179], v188 offset:6144
	s_and_b32 s48, s39, 0x10000
	v_lshlrev_b32_e32 v181, 6, v180
	v_and_b32_e32 v181, 0xfffff000, v181
	v_add_u32_e32 v181, s48, v181
	v_lshlrev_b32_e32 v180, 4, v180
	v_and_or_b32 v189, v180, s3, v181
	v_lshl_add_u64 v[180:181], v[128:129], 0, s[40:41]
	v_readfirstlane_b32 s48, v189
	v_add_u32_e32 v186, 0x8000, v189
	v_lshl_add_u64 v[182:183], v[180:181], 0, s[18:19]
	s_mov_b32 m0, s48
	v_readfirstlane_b32 s48, v186
	global_load_lds_dwordx4 v[182:183], off
	v_lshl_add_u64 v[182:183], v[130:131], 0, s[40:41]
	v_lshl_add_u64 v[184:185], v[182:183], 0, s[20:21]
	s_mov_b32 m0, s48
	v_or_b32_e32 v190, 0x400, v189
	global_load_lds_dwordx4 v[184:185], off
	v_lshl_add_u64 v[184:185], v[132:133], 0, s[40:41]
	v_readfirstlane_b32 s48, v190
	s_waitcnt lgkmcnt(0)
	v_mfma_f32_16x16x32_bf16 v[124:127], v[140:143], v[164:167], v[124:127]
	v_lshl_add_u64 v[186:187], v[184:185], 0, s[22:23]
	s_mov_b32 m0, s48
	v_add_u32_e32 v152, v152, v136
	v_mfma_f32_16x16x32_bf16 v[120:123], v[144:147], v[164:167], v[120:123]
	global_load_lds_dwordx4 v[186:187], off
	v_lshl_add_u64 v[186:187], v[134:135], 0, s[40:41]
	v_mfma_f32_16x16x32_bf16 v[116:119], v[148:151], v[164:167], v[116:119]
	v_mfma_f32_16x16x32_bf16 v[112:115], v[154:157], v[164:167], v[112:115]
	v_add_u32_e32 v166, 0x8400, v189
	v_lshl_add_u64 v[164:165], v[186:187], 0, s[24:25]
	v_readfirstlane_b32 s48, v166
	v_or_b32_e32 v166, 0x800, v189
	s_mov_b32 m0, s48
	v_readfirstlane_b32 s48, v166
	v_add_u32_e32 v166, 0x8800, v189
	global_load_lds_dwordx4 v[164:165], off
	v_lshl_add_u64 v[164:165], v[180:181], 0, s[26:27]
	s_mov_b32 m0, s48
	v_readfirstlane_b32 s48, v166
	v_or_b32_e32 v166, 0xc00, v189
	global_load_lds_dwordx4 v[164:165], off
	v_lshl_add_u64 v[164:165], v[182:183], 0, s[28:29]
	s_mov_b32 m0, s48
	v_readfirstlane_b32 s48, v166
	v_add_u32_e32 v166, 0x8c00, v189
	global_load_lds_dwordx4 v[164:165], off
	v_lshl_add_u64 v[164:165], v[184:185], 0, s[30:31]
	s_mov_b32 m0, s48
	v_readfirstlane_b32 s48, v166
	global_load_lds_dwordx4 v[164:165], off
	v_lshl_add_u64 v[164:165], v[186:187], 0, s[34:35]
	s_mov_b32 m0, s48
	v_mfma_f32_16x16x32_bf16 v[108:111], v[140:143], v[168:171], v[108:111]
	global_load_lds_dwordx4 v[164:165], off
	v_mfma_f32_16x16x32_bf16 v[104:107], v[144:147], v[168:171], v[104:107]
	v_mfma_f32_16x16x32_bf16 v[100:103], v[148:151], v[168:171], v[100:103]
	v_mfma_f32_16x16x32_bf16 v[96:99], v[154:157], v[168:171], v[96:99]
	ds_read_b128 v[164:167], v188 offset:8192
	ds_read_b128 v[168:171], v188 offset:10240
	v_mfma_f32_16x16x32_bf16 v[92:95], v[140:143], v[172:175], v[92:95]
	v_mfma_f32_16x16x32_bf16 v[88:91], v[144:147], v[172:175], v[88:91]
	v_mfma_f32_16x16x32_bf16 v[84:87], v[148:151], v[172:175], v[84:87]
	v_mfma_f32_16x16x32_bf16 v[80:83], v[154:157], v[172:175], v[80:83]
	ds_read_b128 v[172:175], v188 offset:12288
	ds_read_b128 v[180:183], v188 offset:14336
	ds_read_b128 v[184:187], v152 offset:32768
	ds_read_b128 v[188:191], v152 offset:34816
	ds_read_b128 v[192:195], v152 offset:36864
	ds_read_b128 v[196:199], v152 offset:38912
	v_mfma_f32_16x16x32_bf16 v[76:79], v[140:143], v[176:179], v[76:79]
	v_mfma_f32_16x16x32_bf16 v[72:75], v[144:147], v[176:179], v[72:75]
	v_mfma_f32_16x16x32_bf16 v[68:71], v[148:151], v[176:179], v[68:71]
	v_mfma_f32_16x16x32_bf16 v[64:67], v[154:157], v[176:179], v[64:67]
	v_add_u32_e32 v152, v200, v136
	s_waitcnt lgkmcnt(0)
	v_mfma_f32_16x16x32_bf16 v[60:63], v[140:143], v[164:167], v[60:63]
	v_mfma_f32_16x16x32_bf16 v[56:59], v[144:147], v[164:167], v[56:59]
	v_mfma_f32_16x16x32_bf16 v[52:55], v[148:151], v[164:167], v[52:55]
	v_mfma_f32_16x16x32_bf16 v[48:51], v[154:157], v[164:167], v[48:51]
	v_mfma_f32_16x16x32_bf16 v[44:47], v[140:143], v[168:171], v[44:47]
	v_mfma_f32_16x16x32_bf16 v[40:43], v[144:147], v[168:171], v[40:43]
	v_mfma_f32_16x16x32_bf16 v[36:39], v[148:151], v[168:171], v[36:39]
	v_mfma_f32_16x16x32_bf16 v[28:31], v[140:143], v[172:175], v[28:31]
	v_mfma_f32_16x16x32_bf16 v[24:27], v[144:147], v[172:175], v[24:27]
	v_mfma_f32_16x16x32_bf16 v[20:23], v[148:151], v[172:175], v[20:23]
	v_mfma_f32_16x16x32_bf16 v[12:15], v[140:143], v[180:183], v[12:15]
	v_mfma_f32_16x16x32_bf16 v[8:11], v[144:147], v[180:183], v[8:11]
	v_mfma_f32_16x16x32_bf16 v[4:7], v[148:151], v[180:183], v[4:7]
	ds_read_b128 v[140:143], v152
	ds_read_b128 v[144:147], v152 offset:2048
	ds_read_b128 v[148:151], v152 offset:4096
	ds_read_b128 v[164:167], v152 offset:6144
	v_mfma_f32_16x16x32_bf16 v[32:35], v[154:157], v[168:171], v[32:35]
	v_mfma_f32_16x16x32_bf16 v[16:19], v[154:157], v[172:175], v[16:19]
	v_mfma_f32_16x16x32_bf16 v[0:3], v[154:157], v[180:183], v[0:3]
	s_waitcnt lgkmcnt(0)
; __device__ __forceinline__ f32x4 mfma16(bf16x8 a, bf16x8 b, f32x4 c) { return __builtin_amdgcn_mfma_f32_16x16x32_bf16(a, b, c, 0, 0, 0); }
; #define WAIT_V(n) asm volatile("s_waitcnt vmcnt(" #n ")" ::: "memory")
; __device__ __forceinline__ void gemm_mainloop(f32x4 (&acc)[8][4], const GemmSrc& g, int K, char* lds) {
;     ...
;     for (int kt = 0; kt < KT; kt++) {
;         WAIT_V(0);
;         __builtin_amdgcn_s_barrier();
;         const char* st = lds + (kt & 1) * 65536;
;         bf16x8 afA[4], afB[4], bX[4], bY[4];
; #pragma unroll
;         for (int ni = 0; ni < 4; ni++) afA[ni] = *(const bf16x8*)(st + woff + ni * 16 * 128 + rdo0);
; #pragma unroll
;         for (int mi = 0; mi < 4; mi++) bX[mi] = *(const bf16x8*)(st + xoff + mi * 16 * 128 + rdo0);
;         if (kt + 1 < KT) gemm_issue(g, kt + 1, (kt + 1) & 1, lds);
; #pragma unroll
;         for (int mi = 0; mi < 4; mi++) bY[mi] = *(const bf16x8*)(st + xoff + (4 + mi) * 16 * 128 + rdo0);
; #pragma unroll
;         for (int ni = 0; ni < 4; ni++) afB[ni] = *(const bf16x8*)(st + woff + ni * 16 * 128 + rdo1);
; #pragma unroll
;         for (int mi = 0; mi < 4; mi++)
; #pragma unroll
;             for (int ni = 0; ni < 4; ni++) acc[mi][ni] = mfma16(afA[ni], bX[mi], acc[mi][ni]);
;         __builtin_amdgcn_sched_barrier(0);
; #pragma unroll
;         for (int mi = 0; mi < 4; mi++) bX[mi] = *(const bf16x8*)(st + xoff + mi * 16 * 128 + rdo1);
; #pragma unroll
;         for (int mi = 0; mi < 4; mi++)
; #pragma unroll
;             for (int ni = 0; ni < 4; ni++) acc[4 + mi][ni] = mfma16(afA[ni], bY[mi], acc[4 + mi][ni]);
;         __builtin_amdgcn_sched_barrier(0);
; #pragma unroll
;         for (int mi = 0; mi < 4; mi++) bY[mi] = *(const bf16x8*)(st + xoff + (4 + mi) * 16 * 128 + rdo1);
; #pragma unroll
;         for (int mi = 0; mi < 4; mi++)
; #pragma unroll
;             for (int ni = 0; ni < 4; ni++) acc[mi][ni] = mfma16(afB[ni], bX[mi], acc[mi][ni]);
;         __builtin_amdgcn_sched_barrier(0);
; #pragma unroll
;         for (int mi = 0; mi < 4; mi++)
; #pragma unroll
;             for (int ni = 0; ni < 4; ni++) acc[4 + mi][ni] = mfma16(afB[ni], bY[mi], acc[4 + mi][ni]);
;         __builtin_amdgcn_sched_barrier(0);
	v_mfma_f32_16x16x32_bf16 v[124:127], v[184:187], v[140:143], v[124:127]
	v_mfma_f32_16x16x32_bf16 v[120:123], v[188:191], v[140:143], v[120:123]
	v_mfma_f32_16x16x32_bf16 v[116:119], v[192:195], v[140:143], v[116:119]
	v_mfma_f32_16x16x32_bf16 v[112:115], v[196:199], v[140:143], v[112:115]
	v_mfma_f32_16x16x32_bf16 v[108:111], v[184:187], v[144:147], v[108:111]
	v_mfma_f32_16x16x32_bf16 v[104:107], v[188:191], v[144:147], v[104:107]
	v_mfma_f32_16x16x32_bf16 v[100:103], v[192:195], v[144:147], v[100:103]
	v_mfma_f32_16x16x32_bf16 v[96:99], v[196:199], v[144:147], v[96:99]
	v_mfma_f32_16x16x32_bf16 v[92:95], v[184:187], v[148:151], v[92:95]
	v_mfma_f32_16x16x32_bf16 v[88:91], v[188:191], v[148:151], v[88:91]
	v_mfma_f32_16x16x32_bf16 v[84:87], v[192:195], v[148:151], v[84:87]
	v_mfma_f32_16x16x32_bf16 v[80:83], v[196:199], v[148:151], v[80:83]
	ds_read_b128 v[140:143], v152 offset:8192
	ds_read_b128 v[144:147], v152 offset:10240
	ds_read_b128 v[148:151], v152 offset:12288
	ds_read_b128 v[154:157], v152 offset:14336
	v_mfma_f32_16x16x32_bf16 v[76:79], v[184:187], v[164:167], v[76:79]
	v_mfma_f32_16x16x32_bf16 v[72:75], v[188:191], v[164:167], v[72:75]
	v_mfma_f32_16x16x32_bf16 v[68:71], v[192:195], v[164:167], v[68:71]
	v_mfma_f32_16x16x32_bf16 v[64:67], v[196:199], v[164:167], v[64:67]
	s_waitcnt lgkmcnt(0)
	v_mfma_f32_16x16x32_bf16 v[60:63], v[184:187], v[140:143], v[60:63]
	v_mfma_f32_16x16x32_bf16 v[56:59], v[188:191], v[140:143], v[56:59]
	v_mfma_f32_16x16x32_bf16 v[52:55], v[192:195], v[140:143], v[52:55]
	v_mfma_f32_16x16x32_bf16 v[48:51], v[196:199], v[140:143], v[48:51]
	v_mfma_f32_16x16x32_bf16 v[44:47], v[184:187], v[144:147], v[44:47]
	v_mfma_f32_16x16x32_bf16 v[40:43], v[188:191], v[144:147], v[40:43]
	v_mfma_f32_16x16x32_bf16 v[36:39], v[192:195], v[144:147], v[36:39]
	v_mfma_f32_16x16x32_bf16 v[32:35], v[196:199], v[144:147], v[32:35]
	v_mfma_f32_16x16x32_bf16 v[28:31], v[184:187], v[148:151], v[28:31]
	v_mfma_f32_16x16x32_bf16 v[24:27], v[188:191], v[148:151], v[24:27]
	v_mfma_f32_16x16x32_bf16 v[20:23], v[192:195], v[148:151], v[20:23]
	v_mfma_f32_16x16x32_bf16 v[16:19], v[196:199], v[148:151], v[16:19]
	v_mfma_f32_16x16x32_bf16 v[12:15], v[184:187], v[154:157], v[12:15]
	v_mfma_f32_16x16x32_bf16 v[8:11], v[188:191], v[154:157], v[8:11]
	v_mfma_f32_16x16x32_bf16 v[4:7], v[192:195], v[154:157], v[4:7]
	v_mfma_f32_16x16x32_bf16 v[0:3], v[196:199], v[154:157], v[0:3]
	s_add_u32 s40, s40, 0x80
	s_addc_u32 s41, s41, 0
	s_add_i32 s39, s39, 0x10000
	s_cmpk_lg_i32 s40, 0x780
	s_cbranch_scc1 .LBB0_787
	v_or_b32_e32 v150, 0x8000, v139
	v_add_u32_e32 v152, 0x10000, v138
	v_add3_u32 v151, v150, v137, s44
	v_add_u32_e32 v137, v152, v137
	s_waitcnt vmcnt(0)
	s_barrier
	ds_read_b128 v[128:131], v151
	ds_read_b128 v[132:135], v151 offset:2048
	ds_read_b128 v[138:141], v137
	ds_read_b128 v[142:145], v137 offset:2048
	ds_read_b128 v[146:149], v151 offset:4096
	ds_read_b128 v[154:157], v151 offset:6144
	s_waitcnt lgkmcnt(0)
	v_mfma_f32_16x16x32_bf16 v[124:127], v[128:131], v[138:141], v[124:127]
	v_mfma_f32_16x16x32_bf16 v[120:123], v[132:135], v[138:141], v[120:123]
	v_mfma_f32_16x16x32_bf16 v[116:119], v[146:149], v[138:141], v[116:119]
	v_mfma_f32_16x16x32_bf16 v[112:115], v[154:157], v[138:141], v[112:115]
	v_mfma_f32_16x16x32_bf16 v[108:111], v[128:131], v[142:145], v[108:111]
	v_mfma_f32_16x16x32_bf16 v[104:107], v[132:135], v[142:145], v[104:107]
	v_mfma_f32_16x16x32_bf16 v[100:103], v[146:149], v[142:145], v[100:103]
	v_mfma_f32_16x16x32_bf16 v[96:99], v[154:157], v[142:145], v[96:99]
	ds_read_b128 v[138:141], v137 offset:4096
	ds_read_b128 v[142:145], v137 offset:6144
	s_waitcnt lgkmcnt(0)
	v_mfma_f32_16x16x32_bf16 v[92:95], v[128:131], v[138:141], v[92:95]
	v_mfma_f32_16x16x32_bf16 v[88:91], v[132:135], v[138:141], v[88:91]
	v_mfma_f32_16x16x32_bf16 v[84:87], v[146:149], v[138:141], v[84:87]
	v_mfma_f32_16x16x32_bf16 v[80:83], v[154:157], v[138:141], v[80:83]
	v_add3_u32 v138, v150, v136, s44
	ds_read_b128 v[164:167], v138 offset:6144
	ds_read_b128 v[168:171], v138 offset:4096
	ds_read_b128 v[172:175], v138 offset:2048
	ds_read_b128 v[176:179], v138
	ds_read_b128 v[138:141], v137 offset:14336
	ds_read_b128 v[180:183], v137 offset:12288
	ds_read_b128 v[184:187], v137 offset:10240
	ds_read_b128 v[188:191], v137 offset:8192
	v_mfma_f32_16x16x32_bf16 v[76:79], v[128:131], v[142:145], v[76:79]
	v_mfma_f32_16x16x32_bf16 v[72:75], v[132:135], v[142:145], v[72:75]
	v_mfma_f32_16x16x32_bf16 v[68:71], v[146:149], v[142:145], v[68:71]
	v_mfma_f32_16x16x32_bf16 v[192:195], v[154:157], v[142:145], v[64:67]
	v_add_u32_e32 v152, v152, v136
	s_waitcnt lgkmcnt(0)
	v_mfma_f32_16x16x32_bf16 v[52:55], v[146:149], v[188:191], v[52:55]
	v_mfma_f32_16x16x32_bf16 v[36:39], v[146:149], v[184:187], v[36:39]
	v_mfma_f32_16x16x32_bf16 v[28:31], v[128:131], v[180:183], v[28:31]
	v_mfma_f32_16x16x32_bf16 v[24:27], v[132:135], v[180:183], v[24:27]
	v_mfma_f32_16x16x32_bf16 v[20:23], v[146:149], v[180:183], v[20:23]
	v_mfma_f32_16x16x32_bf16 v[16:19], v[154:157], v[180:183], v[16:19]
	v_mfma_f32_16x16x32_bf16 v[4:7], v[146:149], v[138:141], v[4:7]
	ds_read_b128 v[64:67], v152
	ds_read_b128 v[144:147], v152 offset:2048
	ds_read_b128 v[148:151], v152 offset:4096
	ds_read_b128 v[180:183], v152 offset:6144
	v_mfma_f32_16x16x32_bf16 v[0:3], v[154:157], v[138:141], v[0:3]
	v_mfma_f32_16x16x32_bf16 v[60:63], v[128:131], v[188:191], v[60:63]
	v_mfma_f32_16x16x32_bf16 v[56:59], v[132:135], v[188:191], v[56:59]
	v_mfma_f32_16x16x32_bf16 v[48:51], v[154:157], v[188:191], v[48:51]
	v_mfma_f32_16x16x32_bf16 v[44:47], v[128:131], v[184:187], v[44:47]
	v_mfma_f32_16x16x32_bf16 v[40:43], v[132:135], v[184:187], v[40:43]
	v_mfma_f32_16x16x32_bf16 v[32:35], v[154:157], v[184:187], v[32:35]
	v_mfma_f32_16x16x32_bf16 v[12:15], v[128:131], v[138:141], v[12:15]
	v_mfma_f32_16x16x32_bf16 v[8:11], v[132:135], v[138:141], v[8:11]
	s_waitcnt lgkmcnt(0)
; __device__ __forceinline__ f32x4 mfma16(bf16x8 a, bf16x8 b, f32x4 c) { return __builtin_amdgcn_mfma_f32_16x16x32_bf16(a, b, c, 0, 0, 0); }
; __device__ __forceinline__ void gemm_mainloop(f32x4 (&acc)[8][4], const GemmSrc& g, int K, char* lds) {
;     ...
;         for (int mi = 0; mi < 4; mi++)
; #pragma unroll
;             for (int ni = 0; ni < 4; ni++) acc[mi][ni] = mfma16(afB[ni], bX[mi], acc[mi][ni]);
;         __builtin_amdgcn_sched_barrier(0);
; #pragma unroll
;         for (int mi = 0; mi < 4; mi++)
; #pragma unroll
;             for (int ni = 0; ni < 4; ni++) acc[4 + mi][ni] = mfma16(afB[ni], bY[mi], acc[4 + mi][ni]);
; __device__ void phaseM2(const Params& p, char* lds) {
;     ...
;         const int m0 = bm * 256, n0 = bn * 256;
;         f32x4 acc[8][4];
;         zero_acc(acc);
;         gemm_core(acc, M, DM, (const bf16_t*)(p.ws + OFF_WO), DM, DM, m0, n0, lds);
; #pragma unroll
;         for (int mi = 0; mi < 8; mi++)
; #pragma unroll
;             for (int ni = 0; ni < 4; ni++) {
;                 const int tok = m0 + wr * 128 + mi * 16 + r, col = n0 + wc * 64 + ni * 16 + 4 * q;
;                 const f32x4 xv = *(const f32x4*)(p.x + (size_t)tok * DM + col);
;                 const f32x4 gt = *(const f32x4*)(mod + (tok >> 11) * 6144 + 2 * 1024 + col);
;                 epi_fill(lds, wr, wc, r, q, mi, ni, xv + gt * acc[mi][ni]);
;             }
	v_mfma_f32_16x16x32_bf16 v[140:143], v[176:179], v[64:67], v[124:127]
	v_mfma_f32_16x16x32_bf16 v[136:139], v[172:175], v[64:67], v[120:123]
	v_mfma_f32_16x16x32_bf16 v[132:135], v[168:171], v[64:67], v[116:119]
	v_mfma_f32_16x16x32_bf16 v[128:131], v[164:167], v[64:67], v[112:115]
	v_mfma_f32_16x16x32_bf16 v[124:127], v[176:179], v[144:147], v[108:111]
	v_mfma_f32_16x16x32_bf16 v[120:123], v[172:175], v[144:147], v[104:107]
	v_mfma_f32_16x16x32_bf16 v[116:119], v[168:171], v[144:147], v[100:103]
	v_mfma_f32_16x16x32_bf16 v[112:115], v[164:167], v[144:147], v[96:99]
	v_mfma_f32_16x16x32_bf16 v[108:111], v[176:179], v[148:151], v[92:95]
	v_mfma_f32_16x16x32_bf16 v[104:107], v[172:175], v[148:151], v[88:91]
	v_mfma_f32_16x16x32_bf16 v[100:103], v[168:171], v[148:151], v[84:87]
	v_mfma_f32_16x16x32_bf16 v[96:99], v[164:167], v[148:151], v[80:83]
	v_mfma_f32_16x16x32_bf16 v[92:95], v[176:179], v[180:183], v[76:79]
	v_mfma_f32_16x16x32_bf16 v[80:83], v[172:175], v[180:183], v[72:75]
	s_nop 2
	ds_read_b128 v[72:75], v152 offset:8192
	ds_read_b128 v[76:79], v152 offset:10240
	ds_read_b128 v[84:87], v152 offset:12288
	ds_read_b128 v[88:91], v152 offset:14336
	v_mfma_f32_16x16x32_bf16 v[64:67], v[168:171], v[180:183], v[68:71]
	v_mfma_f32_16x16x32_bf16 v[68:71], v[164:167], v[180:183], v[192:195]
	s_waitcnt lgkmcnt(0)
	v_mfma_f32_16x16x32_bf16 v[0:3], v[164:167], v[88:91], v[0:3]
	v_mfma_f32_16x16x32_bf16 v[60:63], v[176:179], v[72:75], v[60:63]
	v_mfma_f32_16x16x32_bf16 v[56:59], v[172:175], v[72:75], v[56:59]
	v_mfma_f32_16x16x32_bf16 v[52:55], v[168:171], v[72:75], v[52:55]
	v_mfma_f32_16x16x32_bf16 v[48:51], v[164:167], v[72:75], v[48:51]
	v_mfma_f32_16x16x32_bf16 v[44:47], v[176:179], v[76:79], v[44:47]
	v_mfma_f32_16x16x32_bf16 v[40:43], v[172:175], v[76:79], v[40:43]
	v_mfma_f32_16x16x32_bf16 v[36:39], v[168:171], v[76:79], v[36:39]
	v_mfma_f32_16x16x32_bf16 v[32:35], v[164:167], v[76:79], v[32:35]
	v_mfma_f32_16x16x32_bf16 v[28:31], v[176:179], v[84:87], v[28:31]
	v_mfma_f32_16x16x32_bf16 v[24:27], v[172:175], v[84:87], v[24:27]
	v_mfma_f32_16x16x32_bf16 v[20:23], v[168:171], v[84:87], v[20:23]
	v_mfma_f32_16x16x32_bf16 v[16:19], v[164:167], v[84:87], v[16:19]
	v_mfma_f32_16x16x32_bf16 v[12:15], v[176:179], v[88:91], v[12:15]
	v_mfma_f32_16x16x32_bf16 v[8:11], v[172:175], v[88:91], v[8:11]
	v_mfma_f32_16x16x32_bf16 v[4:7], v[168:171], v[88:91], v[4:7]
	v_add_u32_e32 v72, s47, v161
	s_waitcnt vmcnt(0)
	s_barrier
	v_or_b32_e32 v154, v72, v160
	v_ashrrev_i32_e32 v72, 11, v72
	s_load_dwordx2 s[40:41], s[8:9], 0x0
	v_mul_i32_i24_e32 v72, 0x1800, v72
	v_ashrrev_i32_e32 v73, 31, v72
	v_or_b32_e32 v84, s38, v162
	v_lshl_add_u64 v[72:73], v[72:73], 2, s[6:7]
	v_ashrrev_i32_e32 v155, 31, v154
	v_lshl_add_u64 v[86:87], v[72:73], 0, s[36:37]
	v_lshlrev_b64 v[72:73], 12, v[154:155]
	v_ashrrev_i32_e32 v85, 31, v84
	v_or_b32_e32 v74, 16, v84
	v_or_b32_e32 v144, 16, v154
	s_waitcnt lgkmcnt(0)
	v_lshl_add_u64 v[72:73], s[40:41], 0, v[72:73]
	v_lshlrev_b64 v[156:157], 2, v[84:85]
	v_ashrrev_i32_e32 v75, 31, v74
	v_or_b32_e32 v90, 32, v84
	v_or_b32_e32 v84, 48, v84
	v_ashrrev_i32_e32 v145, 31, v144
	v_lshl_add_u64 v[88:89], v[72:73], 0, v[156:157]
	v_lshl_add_u64 v[72:73], v[86:87], 0, v[156:157]
	v_lshl_add_u64 v[74:75], v[74:75], 2, v[86:87]
	v_ashrrev_i32_e32 v91, 31, v90
	v_ashrrev_i32_e32 v85, 31, v84
	v_lshlrev_b64 v[144:145], 12, v[144:145]
	global_load_dwordx4 v[164:167], v[88:89], off
	global_load_dwordx4 v[168:171], v[88:89], off offset:64
	global_load_dwordx4 v[76:79], v[72:73], off
	s_nop 0
	global_load_dwordx4 v[72:75], v[74:75], off
	v_lshl_add_u64 v[90:91], v[90:91], 2, v[86:87]
	v_lshl_add_u64 v[84:85], v[84:85], 2, v[86:87]
	v_lshl_add_u64 v[144:145], s[40:41], 0, v[144:145]
	global_load_dwordx4 v[172:175], v[88:89], off offset:128
	global_load_dwordx4 v[176:179], v[88:89], off offset:192
	s_nop 0
	global_load_dwordx4 v[88:91], v[90:91], off
	s_nop 0
	global_load_dwordx4 v[84:87], v[84:85], off
	v_lshl_add_u64 v[144:145], v[144:145], 0, v[156:157]
	global_load_dwordx4 v[180:183], v[144:145], off
	global_load_dwordx4 v[184:187], v[144:145], off offset:64
	global_load_dwordx4 v[188:191], v[144:145], off offset:128
	global_load_dwordx4 v[192:195], v[144:145], off offset:192
	v_or_b32_e32 v144, 32, v154
	v_ashrrev_i32_e32 v145, 31, v144
	v_lshlrev_b64 v[144:145], 12, v[144:145]
	v_lshl_add_u64 v[144:145], s[40:41], 0, v[144:145]
	v_lshl_add_u64 v[144:145], v[144:145], 0, v[156:157]
	global_load_dwordx4 v[196:199], v[144:145], off
	global_load_dwordx4 v[200:203], v[144:145], off offset:64
	v_or_b32_e32 v146, 48, v154
	global_load_dwordx4 v[204:207], v[144:145], off offset:128
	v_ashrrev_i32_e32 v147, 31, v146
	v_lshlrev_b64 v[146:147], 12, v[146:147]
	v_lshl_add_u64 v[146:147], s[40:41], 0, v[146:147]
	v_lshl_add_u64 v[146:147], v[146:147], 0, v[156:157]
	global_load_dwordx4 v[208:211], v[144:145], off offset:192
	global_load_dwordx4 v[212:215], v[146:147], off
	global_load_dwordx4 v[216:219], v[146:147], off offset:64
	global_load_dwordx4 v[148:151], v[146:147], off offset:128
	s_nop 0
	global_load_dwordx4 v[144:147], v[146:147], off offset:192
	v_or_b32_e32 v220, 64, v154
	v_ashrrev_i32_e32 v221, 31, v220
	v_add_u32_e32 v152, 0x4000, v163
	s_waitcnt vmcnt(17)
	v_pk_fma_f32 v[142:143], v[142:143], v[78:79], v[166:167]
	v_pk_fma_f32 v[140:141], v[140:141], v[76:77], v[164:165]
	s_waitcnt vmcnt(16)
	v_pk_fma_f32 v[138:139], v[138:139], v[74:75], v[170:171]
	v_pk_fma_f32 v[136:137], v[136:137], v[72:73], v[168:169]
	v_cvt_pk_bf16_f32 v140, v140, v141
	s_waitcnt vmcnt(11)
	v_pk_fma_f32 v[126:127], v[126:127], v[78:79], v[182:183]
	v_pk_fma_f32 v[124:125], v[124:125], v[76:77], v[180:181]
	s_waitcnt vmcnt(10)
; __device__ __forceinline__ void epi_fill(char* lds, int wr, int wc, int r, int q, int mi, int ni, f32x4 v) {
;     *(u32x2*)(lds + (wr * 128 + mi * 16 + r) * EPI_ROWB + (wc * 64 + ni * 16 + 4 * q) * 2) = (u32x2){pack2(v[0], v[1]), pack2(v[2], v[3])};
; }
; __device__ void phaseM2(const Params& p, char* lds) {
;     ...
; #pragma unroll
;         for (int mi = 0; mi < 8; mi++)
; #pragma unroll
;             for (int ni = 0; ni < 4; ni++) {
;                 const int tok = m0 + wr * 128 + mi * 16 + r, col = n0 + wc * 64 + ni * 16 + 4 * q;
;                 const f32x4 xv = *(const f32x4*)(p.x + (size_t)tok * DM + col);
;                 const f32x4 gt = *(const f32x4*)(mod + (tok >> 11) * 6144 + 2 * 1024 + col);
;                 epi_fill(lds, wr, wc, r, q, mi, ni, xv + gt * acc[mi][ni]);
;             }
	v_pk_fma_f32 v[120:121], v[120:121], v[72:73], v[184:185]
	v_pk_fma_f32 v[134:135], v[134:135], v[90:91], v[174:175]
	v_pk_fma_f32 v[132:133], v[132:133], v[88:89], v[172:173]
	v_pk_fma_f32 v[130:131], v[130:131], v[86:87], v[178:179]
	v_pk_fma_f32 v[128:129], v[128:129], v[84:85], v[176:177]
	v_cvt_pk_bf16_f32 v124, v124, v125
	v_cvt_pk_bf16_f32 v125, v126, v127
	v_cvt_pk_bf16_f32 v126, v120, v121
	v_lshlrev_b64 v[120:121], 12, v[220:221]
	v_pk_fma_f32 v[122:123], v[122:123], v[74:75], v[186:187]
	v_cvt_pk_bf16_f32 v141, v142, v143
	v_cvt_pk_bf16_f32 v136, v136, v137
	v_cvt_pk_bf16_f32 v137, v138, v139
	v_cvt_pk_bf16_f32 v132, v132, v133
	v_cvt_pk_bf16_f32 v133, v134, v135
	v_cvt_pk_bf16_f32 v128, v128, v129
	v_cvt_pk_bf16_f32 v129, v130, v131
	v_lshl_add_u64 v[120:121], s[40:41], 0, v[120:121]
	s_waitcnt vmcnt(9)
	v_pk_fma_f32 v[118:119], v[118:119], v[90:91], v[190:191]
	v_pk_fma_f32 v[116:117], v[116:117], v[88:89], v[188:189]
	v_cvt_pk_bf16_f32 v127, v122, v123
	ds_write2_b64 v163, v[140:141], v[136:137] offset1:4
	ds_write2_b64 v163, v[132:133], v[128:129] offset0:8 offset1:12
	v_lshl_add_u64 v[128:129], v[120:121], 0, v[156:157]
	v_add_u32_e32 v138, 0x2000, v163
	v_cvt_pk_bf16_f32 v132, v116, v117
	v_cvt_pk_bf16_f32 v133, v118, v119
	s_waitcnt vmcnt(8)
	v_pk_fma_f32 v[116:117], v[114:115], v[86:87], v[194:195]
	v_pk_fma_f32 v[118:119], v[112:113], v[84:85], v[192:193]
	global_load_dwordx4 v[120:123], v[128:129], off
	ds_write2_b64 v138, v[124:125], v[126:127] offset0:32 offset1:36
	global_load_dwordx4 v[124:127], v[128:129], off offset:64
	global_load_dwordx4 v[112:115], v[128:129], off offset:128
	v_cvt_pk_bf16_f32 v134, v118, v119
	v_cvt_pk_bf16_f32 v135, v116, v117
	global_load_dwordx4 v[116:119], v[128:129], off offset:192
	v_or_b32_e32 v128, 0x50, v154
	v_ashrrev_i32_e32 v129, 31, v128
	v_lshlrev_b64 v[128:129], 12, v[128:129]
	v_lshl_add_u64 v[128:129], s[40:41], 0, v[128:129]
	ds_write2_b64 v138, v[132:133], v[134:135] offset0:40 offset1:44
	s_waitcnt vmcnt(11)
	v_pk_fma_f32 v[132:133], v[110:111], v[78:79], v[198:199]
	v_lshl_add_u64 v[136:137], v[128:129], 0, v[156:157]
	v_pk_fma_f32 v[134:135], v[108:109], v[76:77], v[196:197]
	v_cvt_pk_bf16_f32 v141, v132, v133
	s_waitcnt vmcnt(10)
	v_pk_fma_f32 v[132:133], v[106:107], v[74:75], v[202:203]
	v_pk_fma_f32 v[104:105], v[104:105], v[72:73], v[200:201]
	global_load_dwordx4 v[128:131], v[136:137], off
	global_load_dwordx4 v[108:111], v[136:137], off offset:64
	v_cvt_pk_bf16_f32 v140, v134, v135
	v_cvt_pk_bf16_f32 v142, v104, v105
	global_load_dwordx4 v[104:107], v[136:137], off offset:128
	v_cvt_pk_bf16_f32 v143, v132, v133
	global_load_dwordx4 v[132:135], v[136:137], off offset:192
	v_or_b32_e32 v136, 0x60, v154
	v_ashrrev_i32_e32 v137, 31, v136
	ds_write2_b64 v152, v[140:141], v[142:143] offset0:64 offset1:68
	s_waitcnt vmcnt(13)
	v_pk_fma_f32 v[140:141], v[102:103], v[90:91], v[206:207]
	v_pk_fma_f32 v[142:143], v[100:101], v[88:89], v[204:205]
	v_or_b32_e32 v154, 0x70, v154
	v_lshlrev_b64 v[136:137], 12, v[136:137]
	v_cvt_pk_bf16_f32 v142, v142, v143
	v_cvt_pk_bf16_f32 v143, v140, v141
	s_waitcnt vmcnt(12)
	v_pk_fma_f32 v[140:141], v[98:99], v[86:87], v[210:211]
	v_pk_fma_f32 v[96:97], v[96:97], v[84:85], v[208:209]
	v_ashrrev_i32_e32 v155, 31, v154
	v_lshl_add_u64 v[136:137], s[40:41], 0, v[136:137]
	v_cvt_pk_bf16_f32 v166, v96, v97
	v_cvt_pk_bf16_f32 v167, v140, v141
	v_lshlrev_b64 v[154:155], 12, v[154:155]
	v_lshl_add_u64 v[164:165], v[136:137], 0, v[156:157]
	ds_write2_b64 v152, v[142:143], v[166:167] offset0:72 offset1:76
	v_lshl_add_u64 v[154:155], s[40:41], 0, v[154:155]
	s_waitcnt vmcnt(11)
	v_pk_fma_f32 v[166:167], v[94:95], v[78:79], v[214:215]
	v_pk_fma_f32 v[92:93], v[92:93], v[76:77], v[212:213]
	s_waitcnt vmcnt(10)
	v_pk_fma_f32 v[82:83], v[82:83], v[74:75], v[218:219]
	v_pk_fma_f32 v[80:81], v[80:81], v[72:73], v[216:217]
	global_load_dwordx4 v[136:139], v[164:165], off
	global_load_dwordx4 v[100:103], v[164:165], off offset:64
	global_load_dwordx4 v[96:99], v[164:165], off offset:128
	global_load_dwordx4 v[140:143], v[164:165], off offset:192
	v_lshl_add_u64 v[164:165], v[154:155], 0, v[156:157]
	v_cvt_pk_bf16_f32 v168, v92, v93
	v_cvt_pk_bf16_f32 v169, v166, v167
	v_cvt_pk_bf16_f32 v166, v80, v81
	v_cvt_pk_bf16_f32 v167, v82, v83
	v_add_u32_e32 v152, 0x6000, v163
	global_load_dwordx4 v[154:157], v[164:165], off
	global_load_dwordx4 v[92:95], v[164:165], off offset:64
	global_load_dwordx4 v[80:83], v[164:165], off offset:128
	ds_write2_b64 v152, v[168:169], v[166:167] offset0:96 offset1:100
	global_load_dwordx4 v[164:167], v[164:165], off offset:192
	s_waitcnt vmcnt(17)
	v_pk_fma_f32 v[66:67], v[66:67], v[90:91], v[150:151]
	v_pk_fma_f32 v[64:65], v[64:65], v[88:89], v[148:149]
	s_waitcnt vmcnt(16)
	v_pk_fma_f32 v[68:69], v[68:69], v[84:85], v[144:145]
	v_cvt_pk_bf16_f32 v64, v64, v65
	v_cvt_pk_bf16_f32 v65, v66, v67
	v_pk_fma_f32 v[66:67], v[70:71], v[86:87], v[146:147]
	v_cvt_pk_bf16_f32 v68, v68, v69
	v_cvt_pk_bf16_f32 v69, v66, v67
	ds_write2_b64 v152, v[64:65], v[68:69] offset0:104 offset1:108
	s_waitcnt vmcnt(15)
	v_pk_fma_f32 v[62:63], v[62:63], v[78:79], v[122:123]
	v_pk_fma_f32 v[60:61], v[60:61], v[76:77], v[120:121]
	s_waitcnt vmcnt(14)
	v_pk_fma_f32 v[58:59], v[58:59], v[74:75], v[126:127]
	v_pk_fma_f32 v[56:57], v[56:57], v[72:73], v[124:125]
	s_waitcnt vmcnt(13)
	v_pk_fma_f32 v[54:55], v[54:55], v[90:91], v[114:115]
	v_pk_fma_f32 v[52:53], v[52:53], v[88:89], v[112:113]
	s_waitcnt vmcnt(12)
; #define TIDX512 launder_i((int)threadIdx.x)
; __device__ __forceinline__ void epi_store(const char* lds, bf16_t* __restrict__ O, int ldo, int m0, int n0, int ncols_valid) {
;     const int t = TIDX512;
;     const int chunk = t & 31, rsub = t >> 5;
;     if (n0 + chunk * 8 < ncols_valid) {
; #pragma unroll
;         for (int ps = 0; ps < 16; ps++) {
;             const int row = ps * 16 + rsub;
;             const u32x4 v = *(const u32x4*)(lds + row * EPI_ROWB + chunk * 16);
;             *(u32x4*)(O + (size_t)(m0 + row) * ldo + n0 + chunk * 8) = v;
;         }
;     }
; }
; __device__ void phaseM2(const Params& p, char* lds) {
;     ...
;                 epi_fill(lds, wr, wc, r, q, mi, ni, xv + gt * acc[mi][ni]);
;             }
;         __syncthreads();
;         epi_store(lds, (bf16_t*)(p.ws + OFF_X1B), DM, m0, n0, DM);
;         __syncthreads();
	v_pk_fma_f32 v[50:51], v[50:51], v[86:87], v[118:119]
	v_pk_fma_f32 v[48:49], v[48:49], v[84:85], v[116:117]
	v_cvt_pk_bf16_f32 v60, v60, v61
	v_cvt_pk_bf16_f32 v61, v62, v63
	v_cvt_pk_bf16_f32 v56, v56, v57
	v_cvt_pk_bf16_f32 v57, v58, v59
	v_add_u32_e32 v58, 0x8000, v163
	v_cvt_pk_bf16_f32 v52, v52, v53
	v_cvt_pk_bf16_f32 v53, v54, v55
	v_cvt_pk_bf16_f32 v48, v48, v49
	v_cvt_pk_bf16_f32 v49, v50, v51
	ds_write2_b64 v58, v[60:61], v[56:57] offset0:128 offset1:132
	s_waitcnt vmcnt(11)
	v_pk_fma_f32 v[46:47], v[46:47], v[78:79], v[130:131]
	v_pk_fma_f32 v[44:45], v[44:45], v[76:77], v[128:129]
	s_waitcnt vmcnt(10)
	v_pk_fma_f32 v[42:43], v[42:43], v[74:75], v[110:111]
	v_pk_fma_f32 v[40:41], v[40:41], v[72:73], v[108:109]
	s_waitcnt vmcnt(9)
	v_pk_fma_f32 v[38:39], v[38:39], v[90:91], v[106:107]
	v_pk_fma_f32 v[36:37], v[36:37], v[88:89], v[104:105]
	s_waitcnt vmcnt(8)
	v_pk_fma_f32 v[34:35], v[34:35], v[86:87], v[134:135]
	v_pk_fma_f32 v[32:33], v[32:33], v[84:85], v[132:133]
	v_cvt_pk_bf16_f32 v44, v44, v45
	v_cvt_pk_bf16_f32 v45, v46, v47
	v_cvt_pk_bf16_f32 v40, v40, v41
	v_cvt_pk_bf16_f32 v41, v42, v43
	v_add_u32_e32 v42, 0xa000, v163
	v_cvt_pk_bf16_f32 v36, v36, v37
	v_cvt_pk_bf16_f32 v37, v38, v39
	v_cvt_pk_bf16_f32 v32, v32, v33
	v_cvt_pk_bf16_f32 v33, v34, v35
	ds_write2_b64 v58, v[52:53], v[48:49] offset0:136 offset1:140
	ds_write2_b64 v42, v[44:45], v[40:41] offset0:160 offset1:164
	ds_write2_b64 v42, v[36:37], v[32:33] offset0:168 offset1:172
	s_waitcnt vmcnt(7)
	v_pk_fma_f32 v[30:31], v[30:31], v[78:79], v[138:139]
	v_pk_fma_f32 v[28:29], v[28:29], v[76:77], v[136:137]
	s_waitcnt vmcnt(6)
	v_pk_fma_f32 v[26:27], v[26:27], v[74:75], v[102:103]
	v_pk_fma_f32 v[24:25], v[24:25], v[72:73], v[100:101]
	s_waitcnt vmcnt(5)
	v_pk_fma_f32 v[22:23], v[22:23], v[90:91], v[98:99]
	v_pk_fma_f32 v[20:21], v[20:21], v[88:89], v[96:97]
	s_waitcnt vmcnt(4)
	v_pk_fma_f32 v[18:19], v[18:19], v[86:87], v[142:143]
	v_pk_fma_f32 v[16:17], v[16:17], v[84:85], v[140:141]
	v_cvt_pk_bf16_f32 v28, v28, v29
	v_cvt_pk_bf16_f32 v29, v30, v31
	s_waitcnt vmcnt(3)
	v_pk_fma_f32 v[14:15], v[14:15], v[78:79], v[156:157]
	v_pk_fma_f32 v[12:13], v[12:13], v[76:77], v[154:155]
	s_waitcnt vmcnt(2)
	v_pk_fma_f32 v[10:11], v[10:11], v[74:75], v[94:95]
	v_pk_fma_f32 v[8:9], v[8:9], v[72:73], v[92:93]
	s_waitcnt vmcnt(1)
	v_pk_fma_f32 v[6:7], v[6:7], v[90:91], v[82:83]
	v_pk_fma_f32 v[4:5], v[4:5], v[88:89], v[80:81]
	s_waitcnt vmcnt(0)
	v_pk_fma_f32 v[2:3], v[2:3], v[86:87], v[166:167]
	v_pk_fma_f32 v[0:1], v[0:1], v[84:85], v[164:165]
	v_cvt_pk_bf16_f32 v24, v24, v25
	v_cvt_pk_bf16_f32 v25, v26, v27
	v_add_u32_e32 v26, 0xc000, v163
	v_cvt_pk_bf16_f32 v20, v20, v21
	v_cvt_pk_bf16_f32 v21, v22, v23
	v_cvt_pk_bf16_f32 v16, v16, v17
	v_cvt_pk_bf16_f32 v17, v18, v19
	v_cvt_pk_bf16_f32 v12, v12, v13
	v_cvt_pk_bf16_f32 v13, v14, v15
	v_cvt_pk_bf16_f32 v8, v8, v9
	v_cvt_pk_bf16_f32 v9, v10, v11
	v_add_u32_e32 v10, 0xe000, v163
	v_cvt_pk_bf16_f32 v4, v4, v5
	v_cvt_pk_bf16_f32 v5, v6, v7
	v_cvt_pk_bf16_f32 v0, v0, v1
	v_cvt_pk_bf16_f32 v1, v2, v3
	v_mov_b32_e32 v2, v158
	ds_write2_b64 v26, v[28:29], v[24:25] offset0:192 offset1:196
	ds_write2_b64 v26, v[20:21], v[16:17] offset0:200 offset1:204
	ds_write2_b64 v10, v[12:13], v[8:9] offset0:224 offset1:228
	ds_write2_b64 v10, v[4:5], v[0:1] offset0:232 offset1:236
	s_waitcnt lgkmcnt(0)
	s_barrier
	s_nop 0
	v_and_b32_e32 v0, 31, v2
	v_lshlrev_b32_e32 v1, 3, v0
	v_or_b32_e32 v3, s38, v1
	v_cmp_gt_i32_e32 vcc, s43, v3
	s_and_saveexec_b64 s[40:41], vcc
	s_cbranch_execz .LBB0_775
	v_ashrrev_i32_e32 v4, 5, v2
	v_lshlrev_b32_e32 v152, 1, v1
	v_mul_lo_u32 v1, v4, s0
	s_ashr_i32 s39, s38, 31
	v_lshl_add_u32 v14, v0, 4, v1
	v_add_u32_e32 v31, 0x10800, v14
	ds_read_b128 v[32:35], v14
	ds_read_b128 v[36:39], v14 offset:8448
	ds_read_b128 v[40:43], v14 offset:16896
	ds_read_b128 v[44:47], v14 offset:25344
	ds_read_b128 v[48:51], v14 offset:33792
	ds_read_b128 v[52:55], v14 offset:42240
	ds_read_b128 v[56:59], v14 offset:50688
	ds_read_b128 v[60:63], v14 offset:59136
	ds_read_b128 v[64:67], v31
	ds_read_b128 v[68:71], v31 offset:8448
	ds_read_b128 v[72:75], v31 offset:16896
	ds_read_b128 v[76:79], v31 offset:25344
	ds_read_b128 v[80:83], v31 offset:33792
	ds_read_b128 v[84:87], v31 offset:42240
	ds_read_b128 v[88:91], v31 offset:50688
	s_lshl_b64 s[38:39], s[38:39], 1
	s_add_u32 s38, s1, s38
	v_add_u32_e32 v10, s47, v4
	s_addc_u32 s39, s2, s39
	v_ashrrev_i32_e32 v11, 31, v10
	v_lshl_add_u64 v[8:9], s[38:39], 0, v[152:153]
	v_lshlrev_b64 v[4:5], 11, v[10:11]
	v_lshl_add_u64 v[12:13], v[8:9], 0, v[4:5]
	s_mov_b64 s[86:87], 0x8000
	s_waitcnt lgkmcnt(14)
	global_store_dwordx4 v[12:13], v[32:35], off
	ds_read_b128 v[92:95], v31 offset:59136
	v_lshl_add_u64 v[12:13], v[12:13], 0, s[86:87]
	s_waitcnt lgkmcnt(14)
	global_store_dwordx4 v[12:13], v[36:39], off
	v_lshl_add_u64 v[12:13], v[12:13], 0, s[86:87]
	s_waitcnt lgkmcnt(13)
	global_store_dwordx4 v[12:13], v[40:43], off
	v_lshl_add_u64 v[12:13], v[12:13], 0, s[86:87]
	s_waitcnt lgkmcnt(12)
	global_store_dwordx4 v[12:13], v[44:47], off
	v_lshl_add_u64 v[12:13], v[12:13], 0, s[86:87]
	s_waitcnt lgkmcnt(11)
	global_store_dwordx4 v[12:13], v[48:51], off
	v_lshl_add_u64 v[12:13], v[12:13], 0, s[86:87]
	s_waitcnt lgkmcnt(10)
	global_store_dwordx4 v[12:13], v[52:55], off
	v_lshl_add_u64 v[12:13], v[12:13], 0, s[86:87]
	s_waitcnt lgkmcnt(9)
	global_store_dwordx4 v[12:13], v[56:59], off
	v_lshl_add_u64 v[12:13], v[12:13], 0, s[86:87]
	s_waitcnt lgkmcnt(8)
	global_store_dwordx4 v[12:13], v[60:63], off
	v_lshl_add_u64 v[12:13], v[12:13], 0, s[86:87]
	s_waitcnt lgkmcnt(7)
	global_store_dwordx4 v[12:13], v[64:67], off
	v_lshl_add_u64 v[12:13], v[12:13], 0, s[86:87]
	s_waitcnt lgkmcnt(6)
	global_store_dwordx4 v[12:13], v[68:71], off
	v_lshl_add_u64 v[12:13], v[12:13], 0, s[86:87]
	s_waitcnt lgkmcnt(5)
	global_store_dwordx4 v[12:13], v[72:75], off
	v_lshl_add_u64 v[12:13], v[12:13], 0, s[86:87]
	s_waitcnt lgkmcnt(4)
	global_store_dwordx4 v[12:13], v[76:79], off
	v_lshl_add_u64 v[12:13], v[12:13], 0, s[86:87]
	s_waitcnt lgkmcnt(3)
	global_store_dwordx4 v[12:13], v[80:83], off
	v_lshl_add_u64 v[12:13], v[12:13], 0, s[86:87]
	s_waitcnt lgkmcnt(2)
	global_store_dwordx4 v[12:13], v[84:87], off
	v_lshl_add_u64 v[12:13], v[12:13], 0, s[86:87]
	s_waitcnt lgkmcnt(1)
	global_store_dwordx4 v[12:13], v[88:91], off
	v_lshl_add_u64 v[12:13], v[12:13], 0, s[86:87]
	s_waitcnt lgkmcnt(0)
	global_store_dwordx4 v[12:13], v[92:95], off
	s_branch .LBB0_775

; #define TIDX512 launder_i((int)threadIdx.x)
; __device__ __forceinline__ void gemm_issue(const GemmSrc& g, int kt, int s, char* lds) {
;     const int tid = TIDX512, lane = tid & 63, wave = tid >> 6;
;     char* xdst = lds + s * 65536 + wave * 4096 + lane * 16;
;     char* wdst = xdst + 32768;
; #pragma unroll
;     for (int i = 0; i < 4; i++) {
;         const int d = (i & 1) ? g.dsw : 0;
; __device__ __forceinline__ void gemm_mainloop(f32x4 (&acc)[8][4], const GemmSrc& g, int K, char* lds) {
;     ...
;     for (int kt = 0; kt < KT; kt++) {
;         WAIT_V(0);
;         __builtin_amdgcn_s_barrier();
;         const char* st = lds + (kt & 1) * 65536;
;         bf16x8 afA[4], afB[4], bX[4], bY[4];
; #pragma unroll
;         for (int ni = 0; ni < 4; ni++) afA[ni] = *(const bf16x8*)(st + woff + ni * 16 * 128 + rdo0);
; #pragma unroll
;         for (int mi = 0; mi < 4; mi++) bX[mi] = *(const bf16x8*)(st + xoff + mi * 16 * 128 + rdo0);
;         if (kt + 1 < KT) gemm_issue(g, kt + 1, (kt + 1) & 1, lds);
; #pragma unroll
;         for (int mi = 0; mi < 4; mi++) bY[mi] = *(const bf16x8*)(st + xoff + (4 + mi) * 16 * 128 + rdo0);
; #pragma unroll
;         for (int ni = 0; ni < 4; ni++) afB[ni] = *(const bf16x8*)(st + woff + ni * 16 * 128 + rdo1);
; #pragma unroll
;         for (int mi = 0; mi < 4; mi++)
; #pragma unroll
;             for (int ni = 0; ni < 4; ni++) acc[mi][ni] = mfma16(afA[ni], bX[mi], acc[mi][ni]);
;         __builtin_amdgcn_sched_barrier(0);
; #pragma unroll
;         for (int mi = 0; mi < 4; mi++) bX[mi] = *(const bf16x8*)(st + xoff + mi * 16 * 128 + rdo1);
; #pragma unroll
;         for (int mi = 0; mi < 4; mi++)
; #pragma unroll
;             for (int ni = 0; ni < 4; ni++) acc[4 + mi][ni] = mfma16(afA[ni], bY[mi], acc[4 + mi][ni]);
;         __builtin_amdgcn_sched_barrier(0);
; #pragma unroll
;         for (int mi = 0; mi < 4; mi++) bY[mi] = *(const bf16x8*)(st + xoff + (4 + mi) * 16 * 128 + rdo1);
; #pragma unroll
;         for (int mi = 0; mi < 4; mi++)
; #pragma unroll
;             for (int ni = 0; ni < 4; ni++) acc[mi][ni] = mfma16(afB[ni], bX[mi], acc[mi][ni]);
;         __builtin_amdgcn_sched_barrier(0);
; #pragma unroll
;         for (int mi = 0; mi < 4; mi++)
; #pragma unroll
;             for (int ni = 0; ni < 4; ni++) acc[4 + mi][ni] = mfma16(afB[ni], bY[mi], acc[4 + mi][ni]);
;         __builtin_amdgcn_sched_barrier(0);
.LBB0_919:
	s_add_i32 s43, s35, 0xffff0000
	s_and_b32 s43, s43, 0x10000
	v_or_b32_e32 v128, s43, v142
	v_add_u32_e32 v143, v128, v140
	s_waitcnt vmcnt(0)
	s_barrier
	ds_read_b128 v[144:147], v143 offset:32768
	ds_read_b128 v[148:151], v143 offset:34816
	ds_read_b128 v[152:155], v143 offset:36864
	ds_read_b128 v[160:163], v143 offset:38912
	v_add_u32_e32 v143, s43, v141
	v_add_u32_e32 v186, v143, v140
	v_mov_b32_e32 v156, v158
	ds_read_b128 v[164:167], v186
	ds_read_b128 v[168:171], v186 offset:2048
	ds_read_b128 v[172:175], v186 offset:4096
	ds_read_b128 v[176:179], v186 offset:6144
	s_and_b32 s43, s35, 0x10000
	v_lshlrev_b32_e32 v157, 6, v156
	v_and_b32_e32 v157, 0xfffff000, v157
	v_add_u32_e32 v157, s43, v157
	v_lshlrev_b32_e32 v156, 4, v156
	v_and_or_b32 v187, v156, s3, v157
	v_lshl_add_u64 v[156:157], v[130:131], 0, s[36:37]
	v_readfirstlane_b32 s43, v187
	v_add_u32_e32 v184, 0x8000, v187
	v_lshl_add_u64 v[180:181], v[156:157], 0, s[16:17]
	s_mov_b32 m0, s43
	v_readfirstlane_b32 s43, v184
	global_load_lds_dwordx4 v[180:181], off
	v_lshl_add_u64 v[180:181], v[132:133], 0, s[36:37]
	v_lshl_add_u64 v[182:183], v[180:181], 0, s[18:19]
	s_mov_b32 m0, s43
	v_or_b32_e32 v188, 0x400, v187
	global_load_lds_dwordx4 v[182:183], off
	v_lshl_add_u64 v[182:183], v[134:135], 0, s[36:37]
	v_readfirstlane_b32 s43, v188
	s_waitcnt lgkmcnt(0)
	v_mfma_f32_16x16x32_bf16 v[124:127], v[144:147], v[164:167], v[124:127]
	v_lshl_add_u64 v[184:185], v[182:183], 0, s[20:21]
	s_mov_b32 m0, s43
	v_lshl_add_u64 v[156:157], v[156:157], 0, s[24:25]
	v_mfma_f32_16x16x32_bf16 v[120:123], v[148:151], v[164:167], v[120:123]
	global_load_lds_dwordx4 v[184:185], off
	v_lshl_add_u64 v[184:185], v[136:137], 0, s[36:37]
	v_mfma_f32_16x16x32_bf16 v[116:119], v[152:155], v[164:167], v[116:119]
	v_add_u32_e32 v128, v128, v139
	v_mfma_f32_16x16x32_bf16 v[112:115], v[160:163], v[164:167], v[112:115]
	v_add_u32_e32 v166, 0x8400, v187
	v_lshl_add_u64 v[164:165], v[184:185], 0, s[22:23]
	v_readfirstlane_b32 s43, v166
	s_mov_b32 m0, s43
	v_mfma_f32_16x16x32_bf16 v[108:111], v[144:147], v[168:171], v[108:111]
	global_load_lds_dwordx4 v[164:165], off
	v_or_b32_e32 v164, 0x800, v187
	v_mfma_f32_16x16x32_bf16 v[104:107], v[148:151], v[168:171], v[104:107]
	v_readfirstlane_b32 s43, v164
	v_add_u32_e32 v164, 0x8800, v187
	s_mov_b32 m0, s43
	v_readfirstlane_b32 s43, v164
	v_or_b32_e32 v164, 0xc00, v187
	global_load_lds_dwordx4 v[156:157], off
	v_lshl_add_u64 v[156:157], v[180:181], 0, s[26:27]
	s_mov_b32 m0, s43
	v_readfirstlane_b32 s43, v164
	v_add_u32_e32 v164, 0x8c00, v187
	global_load_lds_dwordx4 v[156:157], off
	v_lshl_add_u64 v[156:157], v[182:183], 0, s[28:29]
	s_mov_b32 m0, s43
	v_readfirstlane_b32 s43, v164
	global_load_lds_dwordx4 v[156:157], off
	v_lshl_add_u64 v[156:157], v[184:185], 0, s[30:31]
	s_mov_b32 m0, s43
	v_mfma_f32_16x16x32_bf16 v[100:103], v[152:155], v[168:171], v[100:103]
	global_load_lds_dwordx4 v[156:157], off
	v_mfma_f32_16x16x32_bf16 v[96:99], v[160:163], v[168:171], v[96:99]
	ds_read_b128 v[164:167], v186 offset:8192
	ds_read_b128 v[168:171], v186 offset:10240
	v_mfma_f32_16x16x32_bf16 v[92:95], v[144:147], v[172:175], v[92:95]
	v_mfma_f32_16x16x32_bf16 v[88:91], v[148:151], v[172:175], v[88:91]
	v_mfma_f32_16x16x32_bf16 v[84:87], v[152:155], v[172:175], v[84:87]
	v_mfma_f32_16x16x32_bf16 v[80:83], v[160:163], v[172:175], v[80:83]
	ds_read_b128 v[172:175], v186 offset:12288
	ds_read_b128 v[180:183], v186 offset:14336
	ds_read_b128 v[184:187], v128 offset:32768
	ds_read_b128 v[188:191], v128 offset:34816
	ds_read_b128 v[192:195], v128 offset:36864
	ds_read_b128 v[196:199], v128 offset:38912
	v_mfma_f32_16x16x32_bf16 v[76:79], v[144:147], v[176:179], v[76:79]
	v_mfma_f32_16x16x32_bf16 v[72:75], v[148:151], v[176:179], v[72:75]
	v_mfma_f32_16x16x32_bf16 v[68:71], v[152:155], v[176:179], v[68:71]
	v_mfma_f32_16x16x32_bf16 v[64:67], v[160:163], v[176:179], v[64:67]
	v_add_u32_e32 v128, v143, v139
	s_waitcnt lgkmcnt(0)
	v_mfma_f32_16x16x32_bf16 v[60:63], v[144:147], v[164:167], v[60:63]
	v_mfma_f32_16x16x32_bf16 v[56:59], v[148:151], v[164:167], v[56:59]
	v_mfma_f32_16x16x32_bf16 v[52:55], v[152:155], v[164:167], v[52:55]
	v_mfma_f32_16x16x32_bf16 v[48:51], v[160:163], v[164:167], v[48:51]
	v_mfma_f32_16x16x32_bf16 v[44:47], v[144:147], v[168:171], v[44:47]
	v_mfma_f32_16x16x32_bf16 v[40:43], v[148:151], v[168:171], v[40:43]
	v_mfma_f32_16x16x32_bf16 v[36:39], v[152:155], v[168:171], v[36:39]
	v_mfma_f32_16x16x32_bf16 v[28:31], v[144:147], v[172:175], v[28:31]
	v_mfma_f32_16x16x32_bf16 v[24:27], v[148:151], v[172:175], v[24:27]
	v_mfma_f32_16x16x32_bf16 v[20:23], v[152:155], v[172:175], v[20:23]
	v_mfma_f32_16x16x32_bf16 v[12:15], v[144:147], v[180:183], v[12:15]
	v_mfma_f32_16x16x32_bf16 v[8:11], v[148:151], v[180:183], v[8:11]
	v_mfma_f32_16x16x32_bf16 v[4:7], v[152:155], v[180:183], v[4:7]
	ds_read_b128 v[144:147], v128
	ds_read_b128 v[148:151], v128 offset:2048
	ds_read_b128 v[152:155], v128 offset:4096
	ds_read_b128 v[164:167], v128 offset:6144
	v_mfma_f32_16x16x32_bf16 v[32:35], v[160:163], v[168:171], v[32:35]
	v_mfma_f32_16x16x32_bf16 v[16:19], v[160:163], v[172:175], v[16:19]
	v_mfma_f32_16x16x32_bf16 v[0:3], v[160:163], v[180:183], v[0:3]
	s_waitcnt lgkmcnt(0)
; __device__ __forceinline__ f32x4 mfma16(bf16x8 a, bf16x8 b, f32x4 c) { return __builtin_amdgcn_mfma_f32_16x16x32_bf16(a, b, c, 0, 0, 0); }
; #define WAIT_V(n) asm volatile("s_waitcnt vmcnt(" #n ")" ::: "memory")
; __device__ __forceinline__ void gemm_mainloop(f32x4 (&acc)[8][4], const GemmSrc& g, int K, char* lds) {
;     ...
;     for (int kt = 0; kt < KT; kt++) {
;         WAIT_V(0);
;         __builtin_amdgcn_s_barrier();
;         const char* st = lds + (kt & 1) * 65536;
;         bf16x8 afA[4], afB[4], bX[4], bY[4];
; #pragma unroll
;         for (int ni = 0; ni < 4; ni++) afA[ni] = *(const bf16x8*)(st + woff + ni * 16 * 128 + rdo0);
; #pragma unroll
;         for (int mi = 0; mi < 4; mi++) bX[mi] = *(const bf16x8*)(st + xoff + mi * 16 * 128 + rdo0);
;         if (kt + 1 < KT) gemm_issue(g, kt + 1, (kt + 1) & 1, lds);
; #pragma unroll
;         for (int mi = 0; mi < 4; mi++) bY[mi] = *(const bf16x8*)(st + xoff + (4 + mi) * 16 * 128 + rdo0);
; #pragma unroll
;         for (int ni = 0; ni < 4; ni++) afB[ni] = *(const bf16x8*)(st + woff + ni * 16 * 128 + rdo1);
; #pragma unroll
;         for (int mi = 0; mi < 4; mi++)
; #pragma unroll
;             for (int ni = 0; ni < 4; ni++) acc[mi][ni] = mfma16(afA[ni], bX[mi], acc[mi][ni]);
;         __builtin_amdgcn_sched_barrier(0);
; #pragma unroll
;         for (int mi = 0; mi < 4; mi++) bX[mi] = *(const bf16x8*)(st + xoff + mi * 16 * 128 + rdo1);
; #pragma unroll
;         for (int mi = 0; mi < 4; mi++)
; #pragma unroll
;             for (int ni = 0; ni < 4; ni++) acc[4 + mi][ni] = mfma16(afA[ni], bY[mi], acc[4 + mi][ni]);
;         __builtin_amdgcn_sched_barrier(0);
; #pragma unroll
;         for (int mi = 0; mi < 4; mi++) bY[mi] = *(const bf16x8*)(st + xoff + (4 + mi) * 16 * 128 + rdo1);
; #pragma unroll
;         for (int mi = 0; mi < 4; mi++)
; #pragma unroll
;             for (int ni = 0; ni < 4; ni++) acc[mi][ni] = mfma16(afB[ni], bX[mi], acc[mi][ni]);
;         __builtin_amdgcn_sched_barrier(0);
; #pragma unroll
;         for (int mi = 0; mi < 4; mi++)
; #pragma unroll
;             for (int ni = 0; ni < 4; ni++) acc[4 + mi][ni] = mfma16(afB[ni], bY[mi], acc[4 + mi][ni]);
;         __builtin_amdgcn_sched_barrier(0);
	v_mfma_f32_16x16x32_bf16 v[124:127], v[184:187], v[144:147], v[124:127]
	v_mfma_f32_16x16x32_bf16 v[120:123], v[188:191], v[144:147], v[120:123]
	v_mfma_f32_16x16x32_bf16 v[116:119], v[192:195], v[144:147], v[116:119]
	v_mfma_f32_16x16x32_bf16 v[112:115], v[196:199], v[144:147], v[112:115]
	v_mfma_f32_16x16x32_bf16 v[108:111], v[184:187], v[148:151], v[108:111]
	v_mfma_f32_16x16x32_bf16 v[104:107], v[188:191], v[148:151], v[104:107]
	v_mfma_f32_16x16x32_bf16 v[100:103], v[192:195], v[148:151], v[100:103]
	v_mfma_f32_16x16x32_bf16 v[96:99], v[196:199], v[148:151], v[96:99]
	v_mfma_f32_16x16x32_bf16 v[92:95], v[184:187], v[152:155], v[92:95]
	v_mfma_f32_16x16x32_bf16 v[88:91], v[188:191], v[152:155], v[88:91]
	v_mfma_f32_16x16x32_bf16 v[84:87], v[192:195], v[152:155], v[84:87]
	v_mfma_f32_16x16x32_bf16 v[80:83], v[196:199], v[152:155], v[80:83]
	ds_read_b128 v[144:147], v128 offset:8192
	ds_read_b128 v[148:151], v128 offset:10240
	ds_read_b128 v[152:155], v128 offset:12288
	ds_read_b128 v[160:163], v128 offset:14336
	v_mfma_f32_16x16x32_bf16 v[76:79], v[184:187], v[164:167], v[76:79]
	v_mfma_f32_16x16x32_bf16 v[72:75], v[188:191], v[164:167], v[72:75]
	v_mfma_f32_16x16x32_bf16 v[68:71], v[192:195], v[164:167], v[68:71]
	v_mfma_f32_16x16x32_bf16 v[64:67], v[196:199], v[164:167], v[64:67]
	s_waitcnt lgkmcnt(0)
	v_mfma_f32_16x16x32_bf16 v[60:63], v[184:187], v[144:147], v[60:63]
	v_mfma_f32_16x16x32_bf16 v[56:59], v[188:191], v[144:147], v[56:59]
	v_mfma_f32_16x16x32_bf16 v[52:55], v[192:195], v[144:147], v[52:55]
	v_mfma_f32_16x16x32_bf16 v[48:51], v[196:199], v[144:147], v[48:51]
	v_mfma_f32_16x16x32_bf16 v[44:47], v[184:187], v[148:151], v[44:47]
	v_mfma_f32_16x16x32_bf16 v[40:43], v[188:191], v[148:151], v[40:43]
	v_mfma_f32_16x16x32_bf16 v[36:39], v[192:195], v[148:151], v[36:39]
	v_mfma_f32_16x16x32_bf16 v[32:35], v[196:199], v[148:151], v[32:35]
	v_mfma_f32_16x16x32_bf16 v[28:31], v[184:187], v[152:155], v[28:31]
	v_mfma_f32_16x16x32_bf16 v[24:27], v[188:191], v[152:155], v[24:27]
	v_mfma_f32_16x16x32_bf16 v[20:23], v[192:195], v[152:155], v[20:23]
	v_mfma_f32_16x16x32_bf16 v[16:19], v[196:199], v[152:155], v[16:19]
	v_mfma_f32_16x16x32_bf16 v[12:15], v[184:187], v[160:163], v[12:15]
	v_mfma_f32_16x16x32_bf16 v[8:11], v[188:191], v[160:163], v[8:11]
	v_mfma_f32_16x16x32_bf16 v[4:7], v[192:195], v[160:163], v[4:7]
	v_mfma_f32_16x16x32_bf16 v[0:3], v[196:199], v[160:163], v[0:3]
	s_add_u32 s36, s36, 0x80
	s_addc_u32 s37, s37, 0
	s_add_i32 s35, s35, 0x10000
	s_cmpk_lg_i32 s36, 0x780
	s_cbranch_scc1 .LBB0_919
	v_or_b32_e32 v128, 0x8000, v142
	v_add_u32_e32 v156, 0x10000, v141
	v_add3_u32 v152, v128, v140, s40
	v_add_u32_e32 v157, v156, v140
	s_waitcnt vmcnt(0)
	s_barrier
	ds_read_b128 v[130:133], v152
	ds_read_b128 v[134:137], v152 offset:2048
	ds_read_b128 v[140:143], v157
	ds_read_b128 v[144:147], v157 offset:2048
	ds_read_b128 v[148:151], v152 offset:4096
	ds_read_b128 v[152:155], v152 offset:6144
	s_waitcnt lgkmcnt(0)
	v_mfma_f32_16x16x32_bf16 v[124:127], v[130:133], v[140:143], v[124:127]
	v_add3_u32 v128, v128, v139, s40
	v_mfma_f32_16x16x32_bf16 v[120:123], v[134:137], v[140:143], v[120:123]
	v_mfma_f32_16x16x32_bf16 v[116:119], v[148:151], v[140:143], v[116:119]
	v_mfma_f32_16x16x32_bf16 v[112:115], v[152:155], v[140:143], v[112:115]
	v_mfma_f32_16x16x32_bf16 v[108:111], v[130:133], v[144:147], v[108:111]
	v_mfma_f32_16x16x32_bf16 v[104:107], v[134:137], v[144:147], v[104:107]
	v_mfma_f32_16x16x32_bf16 v[100:103], v[148:151], v[144:147], v[100:103]
	v_mfma_f32_16x16x32_bf16 v[96:99], v[152:155], v[144:147], v[96:99]
	ds_read_b128 v[140:143], v157 offset:4096
	ds_read_b128 v[144:147], v157 offset:6144
	s_waitcnt lgkmcnt(0)
	v_mfma_f32_16x16x32_bf16 v[92:95], v[130:133], v[140:143], v[92:95]
	v_mfma_f32_16x16x32_bf16 v[88:91], v[134:137], v[140:143], v[88:91]
	v_mfma_f32_16x16x32_bf16 v[84:87], v[148:151], v[140:143], v[84:87]
	v_mfma_f32_16x16x32_bf16 v[80:83], v[152:155], v[140:143], v[80:83]
	ds_read_b128 v[140:143], v128 offset:6144
	ds_read_b128 v[160:163], v128 offset:4096
	ds_read_b128 v[164:167], v128 offset:2048
	ds_read_b128 v[168:171], v128
	ds_read_b128 v[172:175], v157 offset:14336
	ds_read_b128 v[176:179], v157 offset:12288
	ds_read_b128 v[180:183], v157 offset:10240
	ds_read_b128 v[184:187], v157 offset:8192
	v_mfma_f32_16x16x32_bf16 v[76:79], v[130:133], v[144:147], v[76:79]
	v_mfma_f32_16x16x32_bf16 v[72:75], v[134:137], v[144:147], v[72:75]
	v_mfma_f32_16x16x32_bf16 v[68:71], v[148:151], v[144:147], v[68:71]
	v_mfma_f32_16x16x32_bf16 v[64:67], v[152:155], v[144:147], v[64:67]
	v_add_u32_e32 v128, v156, v139
	s_waitcnt lgkmcnt(0)
	v_mfma_f32_16x16x32_bf16 v[60:63], v[130:133], v[184:187], v[60:63]
	v_mfma_f32_16x16x32_bf16 v[56:59], v[134:137], v[184:187], v[56:59]
	v_mfma_f32_16x16x32_bf16 v[52:55], v[148:151], v[184:187], v[52:55]
	v_mfma_f32_16x16x32_bf16 v[44:47], v[130:133], v[180:183], v[44:47]
	v_mfma_f32_16x16x32_bf16 v[40:43], v[134:137], v[180:183], v[40:43]
	v_mfma_f32_16x16x32_bf16 v[36:39], v[148:151], v[180:183], v[36:39]
	v_mfma_f32_16x16x32_bf16 v[28:31], v[130:133], v[176:179], v[28:31]
	v_mfma_f32_16x16x32_bf16 v[24:27], v[134:137], v[176:179], v[24:27]
	v_mfma_f32_16x16x32_bf16 v[20:23], v[148:151], v[176:179], v[20:23]
	v_mfma_f32_16x16x32_bf16 v[12:15], v[130:133], v[172:175], v[12:15]
	v_mfma_f32_16x16x32_bf16 v[8:11], v[134:137], v[172:175], v[8:11]
	v_mfma_f32_16x16x32_bf16 v[4:7], v[148:151], v[172:175], v[4:7]
	ds_read_b128 v[130:133], v128
	ds_read_b128 v[134:137], v128 offset:2048
	ds_read_b128 v[144:147], v128 offset:4096
	ds_read_b128 v[148:151], v128 offset:6144
	v_mfma_f32_16x16x32_bf16 v[0:3], v[152:155], v[172:175], v[0:3]
	v_mfma_f32_16x16x32_bf16 v[48:51], v[152:155], v[184:187], v[48:51]
	v_mfma_f32_16x16x32_bf16 v[32:35], v[152:155], v[180:183], v[32:35]
	v_mfma_f32_16x16x32_bf16 v[16:19], v[152:155], v[176:179], v[16:19]
	s_waitcnt lgkmcnt(0)
; __device__ __forceinline__ f32x4 mfma16(bf16x8 a, bf16x8 b, f32x4 c) { return __builtin_amdgcn_mfma_f32_16x16x32_bf16(a, b, c, 0, 0, 0); }
; __device__ __forceinline__ void gemm_mainloop(f32x4 (&acc)[8][4], const GemmSrc& g, int K, char* lds) {
;     ...
;         for (int mi = 0; mi < 4; mi++)
; #pragma unroll
;             for (int ni = 0; ni < 4; ni++) acc[mi][ni] = mfma16(afA[ni], bX[mi], acc[mi][ni]);
;         __builtin_amdgcn_sched_barrier(0);
; #pragma unroll
;         for (int mi = 0; mi < 4; mi++) bX[mi] = *(const bf16x8*)(st + xoff + mi * 16 * 128 + rdo1);
; #pragma unroll
;         for (int mi = 0; mi < 4; mi++)
; #pragma unroll
;             for (int ni = 0; ni < 4; ni++) acc[4 + mi][ni] = mfma16(afA[ni], bY[mi], acc[4 + mi][ni]);
;         __builtin_amdgcn_sched_barrier(0);
; #pragma unroll
;         for (int mi = 0; mi < 4; mi++) bY[mi] = *(const bf16x8*)(st + xoff + (4 + mi) * 16 * 128 + rdo1);
; #pragma unroll
;         for (int mi = 0; mi < 4; mi++)
; #pragma unroll
;             for (int ni = 0; ni < 4; ni++) acc[mi][ni] = mfma16(afB[ni], bX[mi], acc[mi][ni]);
;         __builtin_amdgcn_sched_barrier(0);
; #pragma unroll
;         for (int mi = 0; mi < 4; mi++)
; #pragma unroll
;             for (int ni = 0; ni < 4; ni++) acc[4 + mi][ni] = mfma16(afB[ni], bY[mi], acc[4 + mi][ni]);
; __device__ void phaseP1(const Params& p, char* lds) {
;     ...
; #pragma unroll
;         for (int mi = 0; mi < 8; mi++)
; #pragma unroll
;             for (int ni = 0; ni < 4; ni++) epi_fill(lds, wr, wc, r, q, mi, ni, acc[mi][ni]);
	v_mfma_f32_16x16x32_bf16 v[124:127], v[168:171], v[130:133], v[124:127]
	v_mfma_f32_16x16x32_bf16 v[120:123], v[164:167], v[130:133], v[120:123]
	v_mfma_f32_16x16x32_bf16 v[116:119], v[160:163], v[130:133], v[116:119]
	v_mfma_f32_16x16x32_bf16 v[112:115], v[140:143], v[130:133], v[112:115]
	v_mfma_f32_16x16x32_bf16 v[108:111], v[168:171], v[134:137], v[108:111]
	v_mfma_f32_16x16x32_bf16 v[104:107], v[164:167], v[134:137], v[104:107]
	v_mfma_f32_16x16x32_bf16 v[100:103], v[160:163], v[134:137], v[100:103]
	v_mfma_f32_16x16x32_bf16 v[96:99], v[140:143], v[134:137], v[96:99]
	v_mfma_f32_16x16x32_bf16 v[92:95], v[168:171], v[144:147], v[92:95]
	v_mfma_f32_16x16x32_bf16 v[88:91], v[164:167], v[144:147], v[88:91]
	v_mfma_f32_16x16x32_bf16 v[84:87], v[160:163], v[144:147], v[84:87]
	v_mfma_f32_16x16x32_bf16 v[80:83], v[140:143], v[144:147], v[80:83]
	ds_read_b128 v[130:133], v128 offset:8192
	ds_read_b128 v[134:137], v128 offset:10240
	ds_read_b128 v[144:147], v128 offset:12288
	ds_read_b128 v[152:155], v128 offset:14336
	v_mfma_f32_16x16x32_bf16 v[76:79], v[168:171], v[148:151], v[76:79]
	v_mfma_f32_16x16x32_bf16 v[72:75], v[164:167], v[148:151], v[72:75]
	v_mfma_f32_16x16x32_bf16 v[68:71], v[160:163], v[148:151], v[68:71]
	v_mfma_f32_16x16x32_bf16 v[64:67], v[140:143], v[148:151], v[64:67]
	s_waitcnt lgkmcnt(0)
	v_mfma_f32_16x16x32_bf16 v[0:3], v[140:143], v[152:155], v[0:3]
	v_mfma_f32_16x16x32_bf16 v[60:63], v[168:171], v[130:133], v[60:63]
	v_mfma_f32_16x16x32_bf16 v[56:59], v[164:167], v[130:133], v[56:59]
	v_mfma_f32_16x16x32_bf16 v[52:55], v[160:163], v[130:133], v[52:55]
	v_mfma_f32_16x16x32_bf16 v[48:51], v[140:143], v[130:133], v[48:51]
	v_mfma_f32_16x16x32_bf16 v[44:47], v[168:171], v[134:137], v[44:47]
	v_mfma_f32_16x16x32_bf16 v[40:43], v[164:167], v[134:137], v[40:43]
	v_mfma_f32_16x16x32_bf16 v[36:39], v[160:163], v[134:137], v[36:39]
	v_mfma_f32_16x16x32_bf16 v[32:35], v[140:143], v[134:137], v[32:35]
	v_mfma_f32_16x16x32_bf16 v[28:31], v[168:171], v[144:147], v[28:31]
	v_mfma_f32_16x16x32_bf16 v[24:27], v[164:167], v[144:147], v[24:27]
	v_mfma_f32_16x16x32_bf16 v[20:23], v[160:163], v[144:147], v[20:23]
	v_mfma_f32_16x16x32_bf16 v[16:19], v[140:143], v[144:147], v[16:19]
	v_mfma_f32_16x16x32_bf16 v[12:15], v[168:171], v[152:155], v[12:15]
	v_mfma_f32_16x16x32_bf16 v[8:11], v[164:167], v[152:155], v[8:11]
	v_mfma_f32_16x16x32_bf16 v[4:7], v[160:163], v[152:155], v[4:7]
	v_cvt_pk_bf16_f32 v124, v124, v125
	v_cvt_pk_bf16_f32 v125, v126, v127
	v_cvt_pk_bf16_f32 v120, v120, v121
	v_cvt_pk_bf16_f32 v121, v122, v123
	v_cvt_pk_bf16_f32 v116, v116, v117
	v_cvt_pk_bf16_f32 v117, v118, v119
	v_cvt_pk_bf16_f32 v112, v112, v113
	v_cvt_pk_bf16_f32 v113, v114, v115
	v_cvt_pk_bf16_f32 v108, v108, v109
	v_cvt_pk_bf16_f32 v109, v110, v111
	v_cvt_pk_bf16_f32 v104, v104, v105
	v_cvt_pk_bf16_f32 v105, v106, v107
	v_add_u32_e32 v106, 0x2000, v138
	v_cvt_pk_bf16_f32 v100, v100, v101
	v_cvt_pk_bf16_f32 v101, v102, v103
	v_cvt_pk_bf16_f32 v96, v96, v97
	v_cvt_pk_bf16_f32 v97, v98, v99
	v_cvt_pk_bf16_f32 v92, v92, v93
	v_cvt_pk_bf16_f32 v93, v94, v95
	v_cvt_pk_bf16_f32 v88, v88, v89
	v_cvt_pk_bf16_f32 v89, v90, v91
	v_add_u32_e32 v90, 0x4000, v138
	v_cvt_pk_bf16_f32 v84, v84, v85
	v_cvt_pk_bf16_f32 v85, v86, v87
	v_cvt_pk_bf16_f32 v80, v80, v81
	v_cvt_pk_bf16_f32 v81, v82, v83
	v_cvt_pk_bf16_f32 v76, v76, v77
	v_cvt_pk_bf16_f32 v77, v78, v79
	v_cvt_pk_bf16_f32 v72, v72, v73
	v_cvt_pk_bf16_f32 v73, v74, v75
	v_add_u32_e32 v74, 0x6000, v138
	v_cvt_pk_bf16_f32 v68, v68, v69
	v_cvt_pk_bf16_f32 v69, v70, v71
	v_cvt_pk_bf16_f32 v64, v64, v65
	v_cvt_pk_bf16_f32 v65, v66, v67
	v_cvt_pk_bf16_f32 v60, v60, v61
	v_cvt_pk_bf16_f32 v61, v62, v63
	v_cvt_pk_bf16_f32 v56, v56, v57
	v_cvt_pk_bf16_f32 v57, v58, v59
	v_add_u32_e32 v58, 0x8000, v138
	v_cvt_pk_bf16_f32 v52, v52, v53
	v_cvt_pk_bf16_f32 v53, v54, v55
	v_cvt_pk_bf16_f32 v48, v48, v49
	v_cvt_pk_bf16_f32 v49, v50, v51
	v_cvt_pk_bf16_f32 v44, v44, v45
	v_cvt_pk_bf16_f32 v45, v46, v47
	v_cvt_pk_bf16_f32 v40, v40, v41
	v_cvt_pk_bf16_f32 v41, v42, v43
	v_add_u32_e32 v42, 0xa000, v138
	v_cvt_pk_bf16_f32 v36, v36, v37
	v_cvt_pk_bf16_f32 v37, v38, v39
	v_cvt_pk_bf16_f32 v32, v32, v33
	v_cvt_pk_bf16_f32 v33, v34, v35
	v_cvt_pk_bf16_f32 v28, v28, v29
	v_cvt_pk_bf16_f32 v29, v30, v31
	v_cvt_pk_bf16_f32 v24, v24, v25
	v_cvt_pk_bf16_f32 v25, v26, v27
	v_add_u32_e32 v26, 0xc000, v138
	v_cvt_pk_bf16_f32 v20, v20, v21
	v_cvt_pk_bf16_f32 v21, v22, v23
	v_cvt_pk_bf16_f32 v16, v16, v17
	v_cvt_pk_bf16_f32 v17, v18, v19
	v_cvt_pk_bf16_f32 v12, v12, v13
	v_cvt_pk_bf16_f32 v13, v14, v15
	v_cvt_pk_bf16_f32 v8, v8, v9
	v_cvt_pk_bf16_f32 v9, v10, v11
	v_add_u32_e32 v10, 0xe000, v138
	v_cvt_pk_bf16_f32 v4, v4, v5
	v_cvt_pk_bf16_f32 v5, v6, v7
	v_cvt_pk_bf16_f32 v0, v0, v1
	v_cvt_pk_bf16_f32 v1, v2, v3
	v_mov_b32_e32 v2, v158
	s_waitcnt vmcnt(0)
	s_barrier
; #define TIDX512 launder_i((int)threadIdx.x)
; __device__ __forceinline__ void epi_store(const char* lds, bf16_t* __restrict__ O, int ldo, int m0, int n0, int ncols_valid) {
;     const int t = TIDX512;
;     const int chunk = t & 31, rsub = t >> 5;
;     if (n0 + chunk * 8 < ncols_valid) {
; #pragma unroll
;         for (int ps = 0; ps < 16; ps++) {
;             const int row = ps * 16 + rsub;
;             const u32x4 v = *(const u32x4*)(lds + row * EPI_ROWB + chunk * 16);
;             *(u32x4*)(O + (size_t)(m0 + row) * ldo + n0 + chunk * 8) = v;
;         }
;     }
; }
; __device__ void phaseP1(const Params& p, char* lds) {
;     ...
; #pragma unroll
;         for (int mi = 0; mi < 8; mi++)
; #pragma unroll
;             for (int ni = 0; ni < 4; ni++) epi_fill(lds, wr, wc, r, q, mi, ni, acc[mi][ni]);
;         __syncthreads();
;         epi_store(lds, QP, 2048, m0, n0, 2048);
;         __syncthreads();
	ds_write2_b64 v138, v[124:125], v[120:121] offset1:4
	ds_write2_b64 v138, v[116:117], v[112:113] offset0:8 offset1:12
	ds_write2_b64 v106, v[108:109], v[104:105] offset0:32 offset1:36
	ds_write2_b64 v106, v[100:101], v[96:97] offset0:40 offset1:44
	ds_write2_b64 v90, v[92:93], v[88:89] offset0:64 offset1:68
	ds_write2_b64 v90, v[84:85], v[80:81] offset0:72 offset1:76
	ds_write2_b64 v74, v[76:77], v[72:73] offset0:96 offset1:100
	ds_write2_b64 v74, v[68:69], v[64:65] offset0:104 offset1:108
	ds_write2_b64 v58, v[60:61], v[56:57] offset0:128 offset1:132
	ds_write2_b64 v58, v[52:53], v[48:49] offset0:136 offset1:140
	ds_write2_b64 v42, v[44:45], v[40:41] offset0:160 offset1:164
	ds_write2_b64 v42, v[36:37], v[32:33] offset0:168 offset1:172
	ds_write2_b64 v26, v[28:29], v[24:25] offset0:192 offset1:196
	ds_write2_b64 v26, v[20:21], v[16:17] offset0:200 offset1:204
	ds_write2_b64 v10, v[12:13], v[8:9] offset0:224 offset1:228
	ds_write2_b64 v10, v[4:5], v[0:1] offset0:232 offset1:236
	s_waitcnt lgkmcnt(0)
	s_barrier
	s_nop 0
	v_and_b32_e32 v0, 31, v2
	v_lshlrev_b32_e32 v1, 3, v0
	v_or_b32_e32 v3, s34, v1
	v_cmp_gt_i32_e32 vcc, s39, v3
	s_and_saveexec_b64 s[36:37], vcc
	s_cbranch_execz .LBB0_907
	v_ashrrev_i32_e32 v4, 5, v2
	v_lshlrev_b32_e32 v128, 1, v1
	v_mul_lo_u32 v1, v4, s2
	s_ashr_i32 s35, s34, 31
	v_lshl_add_u32 v14, v0, 4, v1
	v_add_u32_e32 v31, 0x10800, v14
	ds_read_b128 v[32:35], v14
	ds_read_b128 v[36:39], v14 offset:8448
	ds_read_b128 v[40:43], v14 offset:16896
	ds_read_b128 v[44:47], v14 offset:25344
	ds_read_b128 v[48:51], v14 offset:33792
	ds_read_b128 v[52:55], v14 offset:42240
	ds_read_b128 v[56:59], v14 offset:50688
	ds_read_b128 v[60:63], v14 offset:59136
	ds_read_b128 v[64:67], v31
	ds_read_b128 v[68:71], v31 offset:8448
	ds_read_b128 v[72:75], v31 offset:16896
	ds_read_b128 v[76:79], v31 offset:25344
	ds_read_b128 v[80:83], v31 offset:33792
	ds_read_b128 v[84:87], v31 offset:42240
	ds_read_b128 v[88:91], v31 offset:50688
	s_lshl_b64 s[34:35], s[34:35], 1
	s_add_u32 s34, s0, s34
	v_add_u32_e32 v10, s42, v4
	s_addc_u32 s35, s1, s35
	v_ashrrev_i32_e32 v11, 31, v10
	v_lshl_add_u64 v[8:9], s[34:35], 0, v[128:129]
	v_lshlrev_b64 v[4:5], 12, v[10:11]
	v_lshl_add_u64 v[12:13], v[8:9], 0, v[4:5]
	s_mov_b64 s[86:87], 0x10000
	s_waitcnt lgkmcnt(14)
	global_store_dwordx4 v[12:13], v[32:35], off
	ds_read_b128 v[92:95], v31 offset:59136
	v_lshl_add_u64 v[12:13], v[12:13], 0, s[86:87]
	s_waitcnt lgkmcnt(14)
	global_store_dwordx4 v[12:13], v[36:39], off
	v_lshl_add_u64 v[12:13], v[12:13], 0, s[86:87]
	s_waitcnt lgkmcnt(13)
	global_store_dwordx4 v[12:13], v[40:43], off
	v_lshl_add_u64 v[12:13], v[12:13], 0, s[86:87]
	s_waitcnt lgkmcnt(12)
	global_store_dwordx4 v[12:13], v[44:47], off
	v_lshl_add_u64 v[12:13], v[12:13], 0, s[86:87]
	s_waitcnt lgkmcnt(11)
	global_store_dwordx4 v[12:13], v[48:51], off
	v_lshl_add_u64 v[12:13], v[12:13], 0, s[86:87]
	s_waitcnt lgkmcnt(10)
	global_store_dwordx4 v[12:13], v[52:55], off
	v_lshl_add_u64 v[12:13], v[12:13], 0, s[86:87]
	s_waitcnt lgkmcnt(9)
	global_store_dwordx4 v[12:13], v[56:59], off
	v_lshl_add_u64 v[12:13], v[12:13], 0, s[86:87]
	s_waitcnt lgkmcnt(8)
	global_store_dwordx4 v[12:13], v[60:63], off
	v_lshl_add_u64 v[12:13], v[12:13], 0, s[86:87]
	s_waitcnt lgkmcnt(7)
	global_store_dwordx4 v[12:13], v[64:67], off
	v_lshl_add_u64 v[12:13], v[12:13], 0, s[86:87]
	s_waitcnt lgkmcnt(6)
	global_store_dwordx4 v[12:13], v[68:71], off
	v_lshl_add_u64 v[12:13], v[12:13], 0, s[86:87]
	s_waitcnt lgkmcnt(5)
	global_store_dwordx4 v[12:13], v[72:75], off
	v_lshl_add_u64 v[12:13], v[12:13], 0, s[86:87]
	s_waitcnt lgkmcnt(4)
	global_store_dwordx4 v[12:13], v[76:79], off
	v_lshl_add_u64 v[12:13], v[12:13], 0, s[86:87]
	s_waitcnt lgkmcnt(3)
	global_store_dwordx4 v[12:13], v[80:83], off
	v_lshl_add_u64 v[12:13], v[12:13], 0, s[86:87]
	s_waitcnt lgkmcnt(2)
	global_store_dwordx4 v[12:13], v[84:87], off
	v_lshl_add_u64 v[12:13], v[12:13], 0, s[86:87]
	s_waitcnt lgkmcnt(1)
	global_store_dwordx4 v[12:13], v[88:91], off
	v_lshl_add_u64 v[12:13], v[12:13], 0, s[86:87]
	s_waitcnt lgkmcnt(0)
	global_store_dwordx4 v[12:13], v[92:95], off
	s_branch .LBB0_907
